# v74 + non-temporal hint on the read-once f32 weight loads (P0 w_in transposes, P3 late-weight transposes)
# speedup vs baseline: 1.0007x; 1.0007x over previous
.Lwi_go:
	s_mul_i32 s2, s16, 0x2620
	s_add_i32 s2, s2, s5
	s_add_i32 s2, s2, s17
	s_lshl_b32 s2, s2, 2
	s_add_u32 s40, s56, s2
	s_addc_u32 s41, s57, 0
	global_load_dwordx4 v[82:85], v6, s[40:41] nt
	s_add_u32 s40, s40, 0x4c400
	s_addc_u32 s41, s41, 0
	global_load_dwordx4 v[86:89], v6, s[40:41] nt
	s_add_u32 s40, s40, 0x4c400
	s_addc_u32 s41, s41, 0
	global_load_dwordx4 v[90:93], v6, s[40:41] nt
	s_add_u32 s40, s40, 0x4c400
	s_addc_u32 s41, s41, 0
	global_load_dwordx4 v[94:97], v6, s[40:41] nt
	s_add_u32 s40, s40, 0x4c400
	s_addc_u32 s41, s41, 0
	global_load_dwordx4 v[98:101], v6, s[40:41] nt
	s_add_u32 s40, s40, 0x4c400
	s_addc_u32 s41, s41, 0
	global_load_dwordx4 v[102:105], v6, s[40:41] nt
	s_add_u32 s40, s40, 0x4c400
	s_addc_u32 s41, s41, 0
	global_load_dwordx4 v[106:109], v6, s[40:41] nt
	s_add_u32 s40, s40, 0x4c400
	s_addc_u32 s41, s41, 0
	global_load_dwordx4 v[110:113], v6, s[40:41] nt

.LBB0_443:
	s_cmpk_gt_u32 s8, 0x7ff
	s_cbranch_scc0 .LBB0_488
	s_cmpk_gt_u32 s8, 0xfff
	s_cbranch_scc0 .LBB0_475
	s_cmpk_gt_u32 s8, 0x3bff
	s_cbranch_scc0 .LBB0_463
	s_and_b32 s0, s8, 0x7fffffc0
	s_and_b32 s2, s10, 0x7e0
	s_add_i32 s6, s0, 0xffffc400
	v_or_b32_e32 v0, s2, v209
	v_add_u32_e32 v204, s6, v210
	v_lshlrev_b32_e32 v192, 2, v0
	s_movk_i32 s0, 0x1600
	v_mov_b32_e32 v0, 0
	v_lshl_add_u64 v[206:207], s[84:85], 0, v[192:193]
	v_cmp_gt_i32_e32 vcc, s0, v204
	v_ashrrev_i32_e32 v205, 31, v204
	v_mov_b32_e32 v1, v0
	v_mov_b32_e32 v2, v0
	v_mov_b32_e32 v3, v0
	s_and_saveexec_b64 s[0:1], vcc
	s_cbranch_execz .LBB0_448
	v_lshlrev_b64 v[0:1], 13, v[204:205]
	v_lshl_add_u64 v[0:1], v[206:207], 0, v[0:1]
	global_load_dwordx4 v[0:3], v[0:1], off nt
.LBB0_448:
	s_or_b64 exec, exec, s[0:1]
	v_mov_b32_e32 v30, s7
	v_mov_b32_e32 v31, s7
	v_mov_b32_e32 v4, s7
	v_mov_b32_e32 v5, s7
	v_mov_b32_e32 v6, s7
	v_mov_b32_e32 v7, s7
	v_mov_b32_e32 v8, s7
	v_mov_b32_e32 v9, s7
	v_mov_b32_e32 v10, s7
	v_mov_b32_e32 v11, s7
	v_mov_b32_e32 v12, s7
	v_mov_b32_e32 v13, s7
	v_mov_b32_e32 v14, s7
	v_mov_b32_e32 v15, s7
	v_mov_b32_e32 v16, s7
	v_mov_b32_e32 v17, s7
	v_mov_b32_e32 v18, s7
	v_mov_b32_e32 v19, s7
	v_mov_b32_e32 v20, s7
	v_mov_b32_e32 v21, s7
	v_mov_b32_e32 v22, s7
	v_mov_b32_e32 v23, s7
	v_mov_b32_e32 v24, s7
	v_mov_b32_e32 v25, s7
	v_mov_b32_e32 v26, s7
	v_mov_b32_e32 v27, s7
	v_mov_b32_e32 v28, s7
	v_mov_b32_e32 v29, s7
	s_movk_i32 s0, 0x15f8
	s_waitcnt vmcnt(0)
	v_mov_b64_e32 v[94:95], v[30:31]
	v_mov_b64_e32 v[62:63], v[30:31]
	v_mov_b64_e32 v[126:127], v[30:31]
	v_mov_b64_e32 v[190:191], v[30:31]
	v_mov_b64_e32 v[158:159], v[30:31]
	v_cmp_gt_i32_e32 vcc, s0, v204
	v_mov_b64_e32 v[90:91], v[26:27]
	v_mov_b64_e32 v[88:89], v[24:25]
	v_mov_b64_e32 v[86:87], v[22:23]
	v_mov_b64_e32 v[84:85], v[20:21]
	v_mov_b64_e32 v[82:83], v[18:19]
	v_mov_b64_e32 v[80:81], v[16:17]
	v_mov_b64_e32 v[78:79], v[14:15]
	v_mov_b64_e32 v[76:77], v[12:13]
	v_mov_b64_e32 v[74:75], v[10:11]
	v_mov_b64_e32 v[72:73], v[8:9]
	v_mov_b64_e32 v[70:71], v[6:7]
	v_mov_b64_e32 v[68:69], v[4:5]
	v_mov_b64_e32 v[66:67], v[2:3]
	v_mov_b64_e32 v[64:65], v[0:1]
	v_mov_b64_e32 v[60:61], v[28:29]
	v_mov_b64_e32 v[54:55], v[22:23]
	v_mov_b64_e32 v[52:53], v[20:21]
	v_mov_b64_e32 v[50:51], v[18:19]
	v_mov_b64_e32 v[48:49], v[16:17]
	v_mov_b64_e32 v[46:47], v[14:15]
	v_mov_b64_e32 v[44:45], v[12:13]
	v_mov_b64_e32 v[42:43], v[10:11]
	v_mov_b64_e32 v[40:41], v[8:9]
	v_mov_b64_e32 v[38:39], v[6:7]
	v_mov_b64_e32 v[36:37], v[4:5]
	v_mov_b64_e32 v[34:35], v[2:3]
	v_mov_b64_e32 v[32:33], v[0:1]
	v_mov_b64_e32 v[124:125], v[28:29]
	v_mov_b64_e32 v[122:123], v[26:27]
	v_mov_b64_e32 v[120:121], v[24:25]
	v_mov_b64_e32 v[114:115], v[18:19]
	v_mov_b64_e32 v[112:113], v[16:17]
	v_mov_b64_e32 v[110:111], v[14:15]
	v_mov_b64_e32 v[108:109], v[12:13]
	v_mov_b64_e32 v[106:107], v[10:11]
	v_mov_b64_e32 v[104:105], v[8:9]
	v_mov_b64_e32 v[102:103], v[6:7]
	v_mov_b64_e32 v[100:101], v[4:5]
	v_mov_b64_e32 v[98:99], v[2:3]
	v_mov_b64_e32 v[96:97], v[0:1]
	v_mov_b64_e32 v[188:189], v[28:29]
	v_mov_b64_e32 v[186:187], v[26:27]
	v_mov_b64_e32 v[184:185], v[24:25]
	v_mov_b64_e32 v[182:183], v[22:23]
	v_mov_b64_e32 v[180:181], v[20:21]
	v_mov_b64_e32 v[174:175], v[14:15]
	v_mov_b64_e32 v[172:173], v[12:13]
	v_mov_b64_e32 v[170:171], v[10:11]
	v_mov_b64_e32 v[168:169], v[8:9]
	v_mov_b64_e32 v[166:167], v[6:7]
	v_mov_b64_e32 v[164:165], v[4:5]
	v_mov_b64_e32 v[162:163], v[2:3]
	v_mov_b64_e32 v[160:161], v[0:1]
	v_mov_b64_e32 v[156:157], v[28:29]
	v_mov_b64_e32 v[154:155], v[26:27]
	v_mov_b64_e32 v[152:153], v[24:25]
	v_mov_b64_e32 v[150:151], v[22:23]
	v_mov_b64_e32 v[148:149], v[20:21]
	v_mov_b64_e32 v[146:147], v[18:19]
	v_mov_b64_e32 v[144:145], v[16:17]
	v_mov_b64_e32 v[142:143], v[14:15]
	v_mov_b64_e32 v[140:141], v[12:13]
	v_mov_b64_e32 v[138:139], v[10:11]
	v_mov_b64_e32 v[136:137], v[8:9]
	v_mov_b64_e32 v[134:135], v[6:7]
	v_mov_b64_e32 v[132:133], v[4:5]
	v_mov_b64_e32 v[130:131], v[2:3]
	v_mov_b64_e32 v[128:129], v[0:1]
	v_mov_b64_e32 v[92:93], v[28:29]
	v_mov_b64_e32 v[58:59], v[26:27]
	v_mov_b64_e32 v[56:57], v[24:25]
	v_mov_b64_e32 v[118:119], v[22:23]
	v_mov_b64_e32 v[116:117], v[20:21]
	v_mov_b64_e32 v[178:179], v[18:19]
	v_mov_b64_e32 v[176:177], v[16:17]
	s_and_saveexec_b64 s[0:1], vcc
	s_cbranch_execz .LBB0_450
	v_lshlrev_b64 v[4:5], 13, v[204:205]
	v_lshl_add_u64 v[4:5], v[206:207], 0, v[4:5]
	v_add_co_u32_e32 v4, vcc, 0x10000, v4
	s_nop 1
	v_addc_co_u32_e32 v5, vcc, 0, v5, vcc
	global_load_dwordx4 v[4:7], v[4:5], off nt
	s_waitcnt vmcnt(0)
	v_mov_b64_e32 v[158:159], v[30:31]
	v_mov_b64_e32 v[138:139], v[10:11]
	v_mov_b64_e32 v[136:137], v[8:9]
	v_mov_b64_e32 v[156:157], v[28:29]
	v_mov_b64_e32 v[154:155], v[26:27]
	v_mov_b64_e32 v[152:153], v[24:25]
	v_mov_b64_e32 v[150:151], v[22:23]
	v_mov_b64_e32 v[148:149], v[20:21]
	v_mov_b64_e32 v[146:147], v[18:19]
	v_mov_b64_e32 v[144:145], v[16:17]
	v_mov_b64_e32 v[142:143], v[14:15]
	v_mov_b64_e32 v[140:141], v[12:13]
	v_mov_b64_e32 v[130:131], v[2:3]
	v_mov_b64_e32 v[128:129], v[0:1]
	v_mov_b32_e32 v136, s7
	v_mov_b32_e32 v137, s7
	v_mov_b32_e32 v138, s7
	v_mov_b32_e32 v139, s7
	v_mov_b64_e32 v[134:135], v[6:7]
	v_mov_b64_e32 v[132:133], v[4:5]
	v_mov_b64_e32 v[190:191], v[158:159]
	v_mov_b64_e32 v[174:175], v[142:143]
	v_mov_b64_e32 v[172:173], v[140:141]
	v_mov_b64_e32 v[160:161], v[128:129]
	v_mov_b64_e32 v[188:189], v[156:157]
	v_mov_b64_e32 v[186:187], v[154:155]
	v_mov_b64_e32 v[184:185], v[152:153]
	v_mov_b64_e32 v[182:183], v[150:151]
	v_mov_b64_e32 v[180:181], v[148:149]
	v_mov_b64_e32 v[178:179], v[146:147]
	v_mov_b64_e32 v[176:177], v[144:145]
	v_mov_b64_e32 v[170:171], v[138:139]
	v_mov_b64_e32 v[168:169], v[136:137]
	v_mov_b64_e32 v[166:167], v[134:135]
	v_mov_b64_e32 v[164:165], v[132:133]
	v_mov_b64_e32 v[162:163], v[130:131]
	v_mov_b32_e32 v172, s7
	v_mov_b32_e32 v173, s7
	v_mov_b32_e32 v174, s7
	v_mov_b32_e32 v175, s7
	v_mov_b64_e32 v[96:97], v[160:161]
	v_mov_b64_e32 v[112:113], v[176:177]
	v_mov_b64_e32 v[114:115], v[178:179]
	v_mov_b64_e32 v[98:99], v[162:163]
	v_mov_b64_e32 v[100:101], v[164:165]
	v_mov_b64_e32 v[102:103], v[166:167]
	v_mov_b64_e32 v[104:105], v[168:169]
	v_mov_b64_e32 v[106:107], v[170:171]
	v_mov_b64_e32 v[108:109], v[172:173]
	v_mov_b64_e32 v[110:111], v[174:175]
	v_mov_b64_e32 v[116:117], v[180:181]
	v_mov_b64_e32 v[118:119], v[182:183]
	v_mov_b64_e32 v[120:121], v[184:185]
	v_mov_b64_e32 v[122:123], v[186:187]
	v_mov_b64_e32 v[124:125], v[188:189]
	v_mov_b64_e32 v[126:127], v[190:191]
	v_mov_b32_e32 v112, s7
	v_mov_b32_e32 v113, s7
	v_mov_b32_e32 v114, s7
	v_mov_b32_e32 v115, s7
	v_mov_b64_e32 v[32:33], v[96:97]
	v_mov_b64_e32 v[52:53], v[116:117]
	v_mov_b64_e32 v[54:55], v[118:119]
	v_mov_b64_e32 v[62:63], v[126:127]
	v_mov_b64_e32 v[34:35], v[98:99]
	v_mov_b64_e32 v[36:37], v[100:101]
	v_mov_b64_e32 v[38:39], v[102:103]
	v_mov_b64_e32 v[40:41], v[104:105]
	v_mov_b64_e32 v[42:43], v[106:107]
	v_mov_b64_e32 v[44:45], v[108:109]
	v_mov_b64_e32 v[46:47], v[110:111]
	v_mov_b64_e32 v[48:49], v[112:113]
	v_mov_b64_e32 v[50:51], v[114:115]
	v_mov_b64_e32 v[56:57], v[120:121]
	v_mov_b64_e32 v[58:59], v[122:123]
	v_mov_b64_e32 v[60:61], v[124:125]
	v_mov_b32_e32 v52, s7
	v_mov_b32_e32 v53, s7
	v_mov_b32_e32 v54, s7
	v_mov_b32_e32 v55, s7
	v_mov_b64_e32 v[94:95], v[62:63]
	v_mov_b64_e32 v[90:91], v[58:59]
	v_mov_b64_e32 v[88:89], v[56:57]
	v_mov_b64_e32 v[64:65], v[32:33]
	v_mov_b64_e32 v[92:93], v[60:61]
	v_mov_b64_e32 v[86:87], v[54:55]
	v_mov_b64_e32 v[84:85], v[52:53]
	v_mov_b64_e32 v[82:83], v[50:51]
	v_mov_b64_e32 v[80:81], v[48:49]
	v_mov_b64_e32 v[78:79], v[46:47]
	v_mov_b64_e32 v[76:77], v[44:45]
	v_mov_b64_e32 v[74:75], v[42:43]
	v_mov_b64_e32 v[72:73], v[40:41]
	v_mov_b64_e32 v[70:71], v[38:39]
	v_mov_b64_e32 v[68:69], v[36:37]
	v_mov_b64_e32 v[66:67], v[34:35]
	v_mov_b32_e32 v88, s7
	v_mov_b32_e32 v89, s7
	v_mov_b32_e32 v90, s7
	v_mov_b32_e32 v91, s7
	v_mov_b64_e32 v[0:1], v[64:65]
	v_mov_b64_e32 v[28:29], v[92:93]
	v_mov_b64_e32 v[30:31], v[94:95]
	v_mov_b64_e32 v[2:3], v[66:67]
	v_mov_b64_e32 v[4:5], v[68:69]
	v_mov_b64_e32 v[6:7], v[70:71]
	v_mov_b64_e32 v[8:9], v[72:73]
	v_mov_b64_e32 v[10:11], v[74:75]
	v_mov_b64_e32 v[12:13], v[76:77]
	v_mov_b64_e32 v[14:15], v[78:79]
	v_mov_b64_e32 v[16:17], v[80:81]
	v_mov_b64_e32 v[18:19], v[82:83]
	v_mov_b64_e32 v[20:21], v[84:85]
	v_mov_b64_e32 v[22:23], v[86:87]
	v_mov_b64_e32 v[24:25], v[88:89]
	v_mov_b64_e32 v[26:27], v[90:91]
	v_mov_b32_e32 v28, s7
	v_mov_b32_e32 v29, s7
	v_mov_b32_e32 v30, s7
	v_mov_b32_e32 v31, s7
.LBB0_450:
	s_or_b64 exec, exec, s[0:1]
	s_movk_i32 s0, 0x15f0
	v_cmp_gt_i32_e32 vcc, s0, v204
	s_and_saveexec_b64 s[0:1], vcc
	s_cbranch_execz .LBB0_452
	v_lshlrev_b64 v[0:1], 13, v[204:205]
	v_lshl_add_u64 v[0:1], v[206:207], 0, v[0:1]
	v_add_co_u32_e32 v0, vcc, 0x20000, v0
	s_nop 1
	v_addc_co_u32_e32 v1, vcc, 0, v1, vcc
	global_load_dwordx4 v[136:139], v[0:1], off nt
	s_waitcnt vmcnt(0)
	v_mov_b64_e32 v[190:191], v[158:159]
	v_mov_b64_e32 v[174:175], v[142:143]
	v_mov_b64_e32 v[172:173], v[140:141]
	v_mov_b64_e32 v[160:161], v[128:129]
	v_mov_b64_e32 v[188:189], v[156:157]
	v_mov_b64_e32 v[186:187], v[154:155]
	v_mov_b64_e32 v[184:185], v[152:153]
	v_mov_b64_e32 v[182:183], v[150:151]
	v_mov_b64_e32 v[180:181], v[148:149]
	v_mov_b64_e32 v[178:179], v[146:147]
	v_mov_b64_e32 v[176:177], v[144:145]
	v_mov_b64_e32 v[166:167], v[134:135]
	v_mov_b64_e32 v[164:165], v[132:133]
	v_mov_b64_e32 v[162:163], v[130:131]
	v_mov_b32_e32 v172, s7
	v_mov_b32_e32 v173, s7
	v_mov_b32_e32 v174, s7
	v_mov_b32_e32 v175, s7
	v_mov_b64_e32 v[170:171], v[138:139]
	v_mov_b64_e32 v[168:169], v[136:137]
	v_mov_b64_e32 v[96:97], v[160:161]
	v_mov_b64_e32 v[112:113], v[176:177]
	v_mov_b64_e32 v[114:115], v[178:179]
	v_mov_b64_e32 v[98:99], v[162:163]
	v_mov_b64_e32 v[100:101], v[164:165]
	v_mov_b64_e32 v[102:103], v[166:167]
	v_mov_b64_e32 v[104:105], v[168:169]
	v_mov_b64_e32 v[106:107], v[170:171]
	v_mov_b64_e32 v[108:109], v[172:173]
	v_mov_b64_e32 v[110:111], v[174:175]
	v_mov_b64_e32 v[116:117], v[180:181]
	v_mov_b64_e32 v[118:119], v[182:183]
	v_mov_b64_e32 v[120:121], v[184:185]
	v_mov_b64_e32 v[122:123], v[186:187]
	v_mov_b64_e32 v[124:125], v[188:189]
	v_mov_b64_e32 v[126:127], v[190:191]
	v_mov_b32_e32 v112, s7
	v_mov_b32_e32 v113, s7
	v_mov_b32_e32 v114, s7
	v_mov_b32_e32 v115, s7
	v_mov_b64_e32 v[32:33], v[96:97]
	v_mov_b64_e32 v[52:53], v[116:117]
	v_mov_b64_e32 v[54:55], v[118:119]
	v_mov_b64_e32 v[62:63], v[126:127]
	v_mov_b64_e32 v[34:35], v[98:99]
	v_mov_b64_e32 v[36:37], v[100:101]
	v_mov_b64_e32 v[38:39], v[102:103]
	v_mov_b64_e32 v[40:41], v[104:105]
	v_mov_b64_e32 v[42:43], v[106:107]
	v_mov_b64_e32 v[44:45], v[108:109]
	v_mov_b64_e32 v[46:47], v[110:111]
	v_mov_b64_e32 v[48:49], v[112:113]
	v_mov_b64_e32 v[50:51], v[114:115]
	v_mov_b64_e32 v[56:57], v[120:121]
	v_mov_b64_e32 v[58:59], v[122:123]
	v_mov_b64_e32 v[60:61], v[124:125]
	v_mov_b32_e32 v52, s7
	v_mov_b32_e32 v53, s7
	v_mov_b32_e32 v54, s7
	v_mov_b32_e32 v55, s7
	v_mov_b64_e32 v[94:95], v[62:63]
	v_mov_b64_e32 v[90:91], v[58:59]
	v_mov_b64_e32 v[88:89], v[56:57]
	v_mov_b64_e32 v[64:65], v[32:33]
	v_mov_b64_e32 v[92:93], v[60:61]
	v_mov_b64_e32 v[86:87], v[54:55]
	v_mov_b64_e32 v[84:85], v[52:53]
	v_mov_b64_e32 v[82:83], v[50:51]
	v_mov_b64_e32 v[80:81], v[48:49]
	v_mov_b64_e32 v[78:79], v[46:47]
	v_mov_b64_e32 v[76:77], v[44:45]
	v_mov_b64_e32 v[74:75], v[42:43]
	v_mov_b64_e32 v[72:73], v[40:41]
	v_mov_b64_e32 v[70:71], v[38:39]
	v_mov_b64_e32 v[68:69], v[36:37]
	v_mov_b64_e32 v[66:67], v[34:35]
	v_mov_b32_e32 v88, s7
	v_mov_b32_e32 v89, s7
	v_mov_b32_e32 v90, s7
	v_mov_b32_e32 v91, s7
	v_mov_b64_e32 v[0:1], v[64:65]
	v_mov_b64_e32 v[28:29], v[92:93]
	v_mov_b64_e32 v[30:31], v[94:95]
	v_mov_b64_e32 v[2:3], v[66:67]
	v_mov_b64_e32 v[4:5], v[68:69]
	v_mov_b64_e32 v[6:7], v[70:71]
	v_mov_b64_e32 v[8:9], v[72:73]
	v_mov_b64_e32 v[10:11], v[74:75]
	v_mov_b64_e32 v[12:13], v[76:77]
	v_mov_b64_e32 v[14:15], v[78:79]
	v_mov_b64_e32 v[16:17], v[80:81]
	v_mov_b64_e32 v[18:19], v[82:83]
	v_mov_b64_e32 v[20:21], v[84:85]
	v_mov_b64_e32 v[22:23], v[86:87]
	v_mov_b64_e32 v[24:25], v[88:89]
	v_mov_b64_e32 v[26:27], v[90:91]
	v_mov_b32_e32 v28, s7
	v_mov_b32_e32 v29, s7
	v_mov_b32_e32 v30, s7
	v_mov_b32_e32 v31, s7
.LBB0_452:
	s_or_b64 exec, exec, s[0:1]
	s_movk_i32 s0, 0x15e8
	v_cmp_gt_i32_e32 vcc, s0, v204
	s_and_saveexec_b64 s[0:1], vcc
	s_cbranch_execz .LBB0_454
	v_lshlrev_b64 v[0:1], 13, v[204:205]
	v_lshl_add_u64 v[0:1], v[206:207], 0, v[0:1]
	v_add_co_u32_e32 v0, vcc, 0x30000, v0
	s_nop 1
	v_addc_co_u32_e32 v1, vcc, 0, v1, vcc
	global_load_dwordx4 v[140:143], v[0:1], off nt
	s_waitcnt vmcnt(0)
	v_mov_b64_e32 v[96:97], v[128:129]
	v_mov_b64_e32 v[112:113], v[144:145]
	v_mov_b64_e32 v[114:115], v[146:147]
	v_mov_b64_e32 v[98:99], v[130:131]
	v_mov_b64_e32 v[100:101], v[132:133]
	v_mov_b64_e32 v[102:103], v[134:135]
	v_mov_b64_e32 v[104:105], v[136:137]
	v_mov_b64_e32 v[106:107], v[138:139]
	v_mov_b64_e32 v[116:117], v[148:149]
	v_mov_b64_e32 v[118:119], v[150:151]
	v_mov_b64_e32 v[120:121], v[152:153]
	v_mov_b64_e32 v[122:123], v[154:155]
	v_mov_b64_e32 v[124:125], v[156:157]
	v_mov_b64_e32 v[126:127], v[158:159]
	v_mov_b32_e32 v112, s7
	v_mov_b32_e32 v113, s7
	v_mov_b32_e32 v114, s7
	v_mov_b32_e32 v115, s7
	v_mov_b64_e32 v[190:191], v[158:159]
	v_mov_b64_e32 v[188:189], v[156:157]
	v_mov_b64_e32 v[186:187], v[154:155]
	v_mov_b64_e32 v[184:185], v[152:153]
	v_mov_b64_e32 v[182:183], v[150:151]
	v_mov_b64_e32 v[180:181], v[148:149]
	v_mov_b64_e32 v[170:171], v[138:139]
	v_mov_b64_e32 v[168:169], v[136:137]
	v_mov_b64_e32 v[166:167], v[134:135]
	v_mov_b64_e32 v[164:165], v[132:133]
	v_mov_b64_e32 v[162:163], v[130:131]
	v_mov_b64_e32 v[160:161], v[128:129]
	v_mov_b64_e32 v[178:179], v[146:147]
	v_mov_b64_e32 v[176:177], v[144:145]
	v_mov_b64_e32 v[108:109], v[140:141]
	v_mov_b64_e32 v[110:111], v[142:143]
	v_mov_b64_e32 v[32:33], v[96:97]
	v_mov_b64_e32 v[52:53], v[116:117]
	v_mov_b64_e32 v[54:55], v[118:119]
	v_mov_b64_e32 v[62:63], v[126:127]
	v_mov_b64_e32 v[34:35], v[98:99]
	v_mov_b64_e32 v[36:37], v[100:101]
	v_mov_b64_e32 v[38:39], v[102:103]
	v_mov_b64_e32 v[40:41], v[104:105]
	v_mov_b64_e32 v[42:43], v[106:107]
	v_mov_b64_e32 v[44:45], v[108:109]
	v_mov_b64_e32 v[46:47], v[110:111]
	v_mov_b64_e32 v[48:49], v[112:113]
	v_mov_b64_e32 v[50:51], v[114:115]
	v_mov_b64_e32 v[56:57], v[120:121]
	v_mov_b64_e32 v[58:59], v[122:123]
	v_mov_b64_e32 v[60:61], v[124:125]
	v_mov_b32_e32 v52, s7
	v_mov_b32_e32 v53, s7
	v_mov_b32_e32 v54, s7
	v_mov_b32_e32 v55, s7
	v_mov_b64_e32 v[94:95], v[62:63]
	v_mov_b64_e32 v[90:91], v[58:59]
	v_mov_b64_e32 v[88:89], v[56:57]
	v_mov_b64_e32 v[64:65], v[32:33]
	v_mov_b64_e32 v[92:93], v[60:61]
	v_mov_b64_e32 v[86:87], v[54:55]
	v_mov_b64_e32 v[84:85], v[52:53]
	v_mov_b64_e32 v[82:83], v[50:51]
	v_mov_b64_e32 v[80:81], v[48:49]
	v_mov_b64_e32 v[78:79], v[46:47]
	v_mov_b64_e32 v[76:77], v[44:45]
	v_mov_b64_e32 v[74:75], v[42:43]
	v_mov_b64_e32 v[72:73], v[40:41]
	v_mov_b64_e32 v[70:71], v[38:39]
	v_mov_b64_e32 v[68:69], v[36:37]
	v_mov_b64_e32 v[66:67], v[34:35]
	v_mov_b32_e32 v88, s7
	v_mov_b32_e32 v89, s7
	v_mov_b32_e32 v90, s7
	v_mov_b32_e32 v91, s7
	v_mov_b64_e32 v[0:1], v[64:65]
	v_mov_b64_e32 v[28:29], v[92:93]
	v_mov_b64_e32 v[30:31], v[94:95]
	v_mov_b64_e32 v[2:3], v[66:67]
	v_mov_b64_e32 v[4:5], v[68:69]
	v_mov_b64_e32 v[6:7], v[70:71]
	v_mov_b64_e32 v[8:9], v[72:73]
	v_mov_b64_e32 v[10:11], v[74:75]
	v_mov_b64_e32 v[12:13], v[76:77]
	v_mov_b64_e32 v[14:15], v[78:79]
	v_mov_b64_e32 v[16:17], v[80:81]
	v_mov_b64_e32 v[18:19], v[82:83]
	v_mov_b64_e32 v[20:21], v[84:85]
	v_mov_b64_e32 v[22:23], v[86:87]
	v_mov_b64_e32 v[24:25], v[88:89]
	v_mov_b64_e32 v[26:27], v[90:91]
	v_mov_b32_e32 v28, s7
	v_mov_b32_e32 v29, s7
	v_mov_b32_e32 v30, s7
	v_mov_b32_e32 v31, s7
	v_mov_b64_e32 v[174:175], v[142:143]
	v_mov_b64_e32 v[172:173], v[140:141]
.LBB0_454:
	s_or_b64 exec, exec, s[0:1]
	s_movk_i32 s0, 0x15e0
	v_cmp_gt_i32_e32 vcc, s0, v204
	s_and_saveexec_b64 s[0:1], vcc
	s_cbranch_execz .LBB0_456
	v_lshlrev_b64 v[0:1], 13, v[204:205]
	v_lshl_add_u64 v[0:1], v[206:207], 0, v[0:1]
	v_add_co_u32_e32 v0, vcc, 0x40000, v0
	s_nop 1
	v_addc_co_u32_e32 v1, vcc, 0, v1, vcc
	global_load_dwordx4 v[176:179], v[0:1], off nt
	s_waitcnt vmcnt(0)
	v_mov_b64_e32 v[32:33], v[160:161]
	v_mov_b64_e32 v[52:53], v[180:181]
	v_mov_b64_e32 v[54:55], v[182:183]
	v_mov_b64_e32 v[62:63], v[190:191]
	v_mov_b64_e32 v[34:35], v[162:163]
	v_mov_b64_e32 v[36:37], v[164:165]
	v_mov_b64_e32 v[38:39], v[166:167]
	v_mov_b64_e32 v[40:41], v[168:169]
	v_mov_b64_e32 v[42:43], v[170:171]
	v_mov_b64_e32 v[44:45], v[172:173]
	v_mov_b64_e32 v[46:47], v[174:175]
	v_mov_b64_e32 v[56:57], v[184:185]
	v_mov_b64_e32 v[58:59], v[186:187]
	v_mov_b64_e32 v[60:61], v[188:189]
	v_mov_b32_e32 v52, s7
	v_mov_b32_e32 v53, s7
	v_mov_b32_e32 v54, s7
	v_mov_b32_e32 v55, s7
	v_mov_b64_e32 v[96:97], v[160:161]
	v_mov_b64_e32 v[98:99], v[162:163]
	v_mov_b64_e32 v[100:101], v[164:165]
	v_mov_b64_e32 v[102:103], v[166:167]
	v_mov_b64_e32 v[104:105], v[168:169]
	v_mov_b64_e32 v[106:107], v[170:171]
	v_mov_b64_e32 v[108:109], v[172:173]
	v_mov_b64_e32 v[110:111], v[174:175]
	v_mov_b64_e32 v[120:121], v[184:185]
	v_mov_b64_e32 v[122:123], v[186:187]
	v_mov_b64_e32 v[124:125], v[188:189]
	v_mov_b64_e32 v[126:127], v[190:191]
	v_mov_b64_e32 v[116:117], v[180:181]
	v_mov_b64_e32 v[118:119], v[182:183]
	v_mov_b64_e32 v[48:49], v[176:177]
	v_mov_b64_e32 v[50:51], v[178:179]
	v_mov_b64_e32 v[94:95], v[62:63]
	v_mov_b64_e32 v[90:91], v[58:59]
	v_mov_b64_e32 v[88:89], v[56:57]
	v_mov_b64_e32 v[64:65], v[32:33]
	v_mov_b64_e32 v[92:93], v[60:61]
	v_mov_b64_e32 v[86:87], v[54:55]
	v_mov_b64_e32 v[84:85], v[52:53]
	v_mov_b64_e32 v[82:83], v[50:51]
	v_mov_b64_e32 v[80:81], v[48:49]
	v_mov_b64_e32 v[78:79], v[46:47]
	v_mov_b64_e32 v[76:77], v[44:45]
	v_mov_b64_e32 v[74:75], v[42:43]
	v_mov_b64_e32 v[72:73], v[40:41]
	v_mov_b64_e32 v[70:71], v[38:39]
	v_mov_b64_e32 v[68:69], v[36:37]
	v_mov_b64_e32 v[66:67], v[34:35]
	v_mov_b32_e32 v88, s7
	v_mov_b32_e32 v89, s7
	v_mov_b32_e32 v90, s7
	v_mov_b32_e32 v91, s7
	v_mov_b64_e32 v[0:1], v[64:65]
	v_mov_b64_e32 v[28:29], v[92:93]
	v_mov_b64_e32 v[30:31], v[94:95]
	v_mov_b64_e32 v[2:3], v[66:67]
	v_mov_b64_e32 v[4:5], v[68:69]
	v_mov_b64_e32 v[6:7], v[70:71]
	v_mov_b64_e32 v[8:9], v[72:73]
	v_mov_b64_e32 v[10:11], v[74:75]
	v_mov_b64_e32 v[12:13], v[76:77]
	v_mov_b64_e32 v[14:15], v[78:79]
	v_mov_b64_e32 v[16:17], v[80:81]
	v_mov_b64_e32 v[18:19], v[82:83]
	v_mov_b64_e32 v[20:21], v[84:85]
	v_mov_b64_e32 v[22:23], v[86:87]
	v_mov_b64_e32 v[24:25], v[88:89]
	v_mov_b64_e32 v[26:27], v[90:91]
	v_mov_b32_e32 v28, s7
	v_mov_b32_e32 v29, s7
	v_mov_b32_e32 v30, s7
	v_mov_b32_e32 v31, s7
	v_mov_b64_e32 v[112:113], v[176:177]
	v_mov_b64_e32 v[114:115], v[178:179]
.LBB0_456:
	s_or_b64 exec, exec, s[0:1]
	s_movk_i32 s0, 0x15d8
	v_cmp_gt_i32_e32 vcc, s0, v204
	s_and_saveexec_b64 s[0:1], vcc
	s_cbranch_execz .LBB0_458
	v_lshlrev_b64 v[0:1], 13, v[204:205]
	v_lshl_add_u64 v[0:1], v[206:207], 0, v[0:1]
	v_add_co_u32_e32 v0, vcc, 0x50000, v0
	s_nop 1
	v_addc_co_u32_e32 v1, vcc, 0, v1, vcc
	global_load_dwordx4 v[116:119], v[0:1], off nt
	s_waitcnt vmcnt(0)
	v_mov_b64_e32 v[64:65], v[96:97]
	v_mov_b64_e32 v[88:89], v[120:121]
	v_mov_b64_e32 v[90:91], v[122:123]
	v_mov_b64_e32 v[66:67], v[98:99]
	v_mov_b64_e32 v[68:69], v[100:101]
	v_mov_b64_e32 v[70:71], v[102:103]
	v_mov_b64_e32 v[72:73], v[104:105]
	v_mov_b64_e32 v[74:75], v[106:107]
	v_mov_b64_e32 v[76:77], v[108:109]
	v_mov_b64_e32 v[78:79], v[110:111]
	v_mov_b64_e32 v[80:81], v[112:113]
	v_mov_b64_e32 v[82:83], v[114:115]
	v_mov_b64_e32 v[92:93], v[124:125]
	v_mov_b64_e32 v[94:95], v[126:127]
	v_mov_b32_e32 v88, s7
	v_mov_b32_e32 v89, s7
	v_mov_b32_e32 v90, s7
	v_mov_b32_e32 v91, s7
	v_mov_b64_e32 v[32:33], v[96:97]
	v_mov_b64_e32 v[34:35], v[98:99]
	v_mov_b64_e32 v[36:37], v[100:101]
	v_mov_b64_e32 v[38:39], v[102:103]
	v_mov_b64_e32 v[40:41], v[104:105]
	v_mov_b64_e32 v[42:43], v[106:107]
	v_mov_b64_e32 v[44:45], v[108:109]
	v_mov_b64_e32 v[46:47], v[110:111]
	v_mov_b64_e32 v[48:49], v[112:113]
	v_mov_b64_e32 v[50:51], v[114:115]
	v_mov_b64_e32 v[60:61], v[124:125]
	v_mov_b64_e32 v[62:63], v[126:127]
	v_mov_b64_e32 v[56:57], v[120:121]
	v_mov_b64_e32 v[58:59], v[122:123]
	v_mov_b64_e32 v[84:85], v[116:117]
	v_mov_b64_e32 v[86:87], v[118:119]
	v_mov_b64_e32 v[0:1], v[64:65]
	v_mov_b64_e32 v[28:29], v[92:93]
	v_mov_b64_e32 v[30:31], v[94:95]
	v_mov_b64_e32 v[2:3], v[66:67]
	v_mov_b64_e32 v[4:5], v[68:69]
	v_mov_b64_e32 v[6:7], v[70:71]
	v_mov_b64_e32 v[8:9], v[72:73]
	v_mov_b64_e32 v[10:11], v[74:75]
	v_mov_b64_e32 v[12:13], v[76:77]
	v_mov_b64_e32 v[14:15], v[78:79]
	v_mov_b64_e32 v[16:17], v[80:81]
	v_mov_b64_e32 v[18:19], v[82:83]
	v_mov_b64_e32 v[20:21], v[84:85]
	v_mov_b64_e32 v[22:23], v[86:87]
	v_mov_b64_e32 v[24:25], v[88:89]
	v_mov_b64_e32 v[26:27], v[90:91]
	v_mov_b32_e32 v28, s7
	v_mov_b32_e32 v29, s7
	v_mov_b32_e32 v30, s7
	v_mov_b32_e32 v31, s7
	v_mov_b64_e32 v[52:53], v[116:117]
	v_mov_b64_e32 v[54:55], v[118:119]
.LBB0_458:
	s_or_b64 exec, exec, s[0:1]
	s_movk_i32 s0, 0x15d0
	v_cmp_gt_i32_e32 vcc, s0, v204
	s_and_saveexec_b64 s[0:1], vcc
	s_cbranch_execz .LBB0_460
	v_lshlrev_b64 v[0:1], 13, v[204:205]
	v_lshl_add_u64 v[0:1], v[206:207], 0, v[0:1]
	v_add_co_u32_e32 v0, vcc, 0x60000, v0
	s_nop 1
	v_addc_co_u32_e32 v1, vcc, 0, v1, vcc
	global_load_dwordx4 v[56:59], v[0:1], off nt
	s_waitcnt vmcnt(0)
	v_mov_b64_e32 v[0:1], v[32:33]
	v_mov_b64_e32 v[28:29], v[60:61]
	v_mov_b64_e32 v[30:31], v[62:63]
	v_mov_b64_e32 v[94:95], v[62:63]
	v_mov_b64_e32 v[2:3], v[34:35]
	v_mov_b64_e32 v[4:5], v[36:37]
	v_mov_b64_e32 v[6:7], v[38:39]
	v_mov_b64_e32 v[8:9], v[40:41]
	v_mov_b64_e32 v[10:11], v[42:43]
	v_mov_b64_e32 v[12:13], v[44:45]
	v_mov_b64_e32 v[14:15], v[46:47]
	v_mov_b64_e32 v[16:17], v[48:49]
	v_mov_b64_e32 v[18:19], v[50:51]
	v_mov_b64_e32 v[20:21], v[52:53]
	v_mov_b64_e32 v[22:23], v[54:55]
	v_mov_b32_e32 v28, s7
	v_mov_b32_e32 v29, s7
	v_mov_b32_e32 v30, s7
	v_mov_b32_e32 v31, s7
	v_mov_b64_e32 v[86:87], v[54:55]
	v_mov_b64_e32 v[84:85], v[52:53]
	v_mov_b64_e32 v[82:83], v[50:51]
	v_mov_b64_e32 v[80:81], v[48:49]
	v_mov_b64_e32 v[78:79], v[46:47]
	v_mov_b64_e32 v[76:77], v[44:45]
	v_mov_b64_e32 v[74:75], v[42:43]
	v_mov_b64_e32 v[72:73], v[40:41]
	v_mov_b64_e32 v[70:71], v[38:39]
	v_mov_b64_e32 v[68:69], v[36:37]
	v_mov_b64_e32 v[66:67], v[34:35]
	v_mov_b64_e32 v[64:65], v[32:33]
	v_mov_b64_e32 v[92:93], v[60:61]
	v_mov_b64_e32 v[24:25], v[56:57]
	v_mov_b64_e32 v[26:27], v[58:59]
	v_mov_b64_e32 v[90:91], v[58:59]
	v_mov_b64_e32 v[88:89], v[56:57]
.LBB0_460:
	s_or_b64 exec, exec, s[0:1]
	s_movk_i32 s0, 0x15c8
	v_cmp_gt_i32_e32 vcc, s0, v204
	s_and_saveexec_b64 s[0:1], vcc
	s_cbranch_execz .LBB0_462
	v_lshlrev_b64 v[0:1], 13, v[204:205]
	v_lshl_add_u64 v[0:1], v[206:207], 0, v[0:1]
	v_add_co_u32_e32 v0, vcc, 0x70000, v0
	s_nop 1
	v_addc_co_u32_e32 v1, vcc, 0, v1, vcc
	global_load_dwordx4 v[92:95], v[0:1], off nt
	s_waitcnt vmcnt(0)
	v_mov_b64_e32 v[0:1], v[64:65]
	v_mov_b64_e32 v[2:3], v[66:67]
	v_mov_b64_e32 v[4:5], v[68:69]
	v_mov_b64_e32 v[6:7], v[70:71]
	v_mov_b64_e32 v[8:9], v[72:73]
	v_mov_b64_e32 v[10:11], v[74:75]
	v_mov_b64_e32 v[12:13], v[76:77]
	v_mov_b64_e32 v[14:15], v[78:79]
	v_mov_b64_e32 v[16:17], v[80:81]
	v_mov_b64_e32 v[18:19], v[82:83]
	v_mov_b64_e32 v[20:21], v[84:85]
	v_mov_b64_e32 v[22:23], v[86:87]
	v_mov_b64_e32 v[24:25], v[88:89]
	v_mov_b64_e32 v[26:27], v[90:91]
	v_mov_b64_e32 v[28:29], v[92:93]
	v_mov_b64_e32 v[30:31], v[94:95]

.LBB0_463:
	s_and_b64 vcc, exec, s[0:1]
	s_cbranch_vccz .LBB0_536
	s_add_i32 s0, s8, 0xf000
	s_and_b32 s1, s0, 0xffff
	s_mul_i32 s1, s1, 0xba2f
	s_lshr_b32 s1, s1, 24
	s_lshl_b32 s2, s1, 6
	s_mulk_i32 s1, 0x160
	s_sub_i32 s0, s0, s1
	s_lshl_b32 s3, s0, 5
	s_bfe_i32 s1, s0, 0x10002
	s_lshl_b32 s0, s0, 4
	s_and_b32 s1, s1, 0x1600
	s_and_b32 s0, s0, 0x1f80
	s_add_i32 s1, s1, s0
	s_and_b32 s0, s3, 0x60
	s_or_b32 s0, s1, s0
	v_or_b32_e32 v0, s0, v209
	v_readlane_b32 s36, v235, 1
	v_add_u32_e32 v206, s2, v210
	v_lshlrev_b32_e32 v192, 2, v0
	v_readlane_b32 s50, v235, 15
	v_readlane_b32 s51, v235, 16
	v_mov_b32_e32 v0, 0
	v_cmp_gt_i32_e32 vcc, s20, v206
	v_lshl_add_u64 v[204:205], s[50:51], 0, v[192:193]
	v_mov_b32_e32 v1, v0
	v_mov_b32_e32 v2, v0
	v_mov_b32_e32 v3, v0
	v_readlane_b32 s37, v235, 2
	v_readlane_b32 s38, v235, 3
	v_readlane_b32 s39, v235, 4
	v_readlane_b32 s40, v235, 5
	v_readlane_b32 s41, v235, 6
	v_readlane_b32 s42, v235, 7
	v_readlane_b32 s43, v235, 8
	v_readlane_b32 s44, v235, 9
	v_readlane_b32 s45, v235, 10
	v_readlane_b32 s46, v235, 11
	v_readlane_b32 s47, v235, 12
	v_readlane_b32 s48, v235, 13
	v_readlane_b32 s49, v235, 14
	s_and_saveexec_b64 s[0:1], vcc
	s_cbranch_execz .LBB0_466
	v_mad_i64_i32 v[0:1], s[4:5], v206, s21, v[204:205]
	global_load_dwordx4 v[0:3], v[0:1], off nt

.LBB0_473:
	v_add_u32_e32 v0, 56, v206
	v_mad_i64_i32 v[0:1], s[4:5], v0, s21, v[204:205]
	global_load_dwordx4 v[124:127], v[0:1], off nt
	s_waitcnt vmcnt(0)
	v_mov_b64_e32 v[0:1], v[96:97]
	v_mov_b64_e32 v[2:3], v[98:99]
	v_mov_b64_e32 v[4:5], v[100:101]
	v_mov_b64_e32 v[6:7], v[102:103]
	v_mov_b64_e32 v[8:9], v[104:105]
	v_mov_b64_e32 v[10:11], v[106:107]
	v_mov_b64_e32 v[12:13], v[108:109]
	v_mov_b64_e32 v[14:15], v[110:111]
	v_mov_b64_e32 v[16:17], v[112:113]
	v_mov_b64_e32 v[18:19], v[114:115]
	v_mov_b64_e32 v[20:21], v[116:117]
	v_mov_b64_e32 v[22:23], v[118:119]
	v_mov_b64_e32 v[24:25], v[120:121]
	v_mov_b64_e32 v[26:27], v[122:123]
	v_mov_b64_e32 v[28:29], v[124:125]
	v_mov_b64_e32 v[30:31], v[126:127]

.LBB0_476:
	s_and_b32 s0, s8, 0xfc0
	s_and_b32 s2, s10, 0x7e0
	s_add_i32 s6, s0, 0xfffff800
	v_or_b32_e32 v0, s2, v209
	v_readlane_b32 s36, v235, 1
	v_add_u32_e32 v204, s6, v210
	v_lshlrev_b32_e32 v192, 2, v0
	v_readlane_b32 s46, v235, 11
	v_readlane_b32 s47, v235, 12
	v_mov_b32_e32 v0, 0
	v_cmp_gt_i32_e32 vcc, s20, v204
	v_lshl_add_u64 v[206:207], s[46:47], 0, v[192:193]
	v_ashrrev_i32_e32 v205, 31, v204
	v_mov_b32_e32 v1, v0
	v_mov_b32_e32 v2, v0
	v_mov_b32_e32 v3, v0
	v_readlane_b32 s37, v235, 2
	v_readlane_b32 s38, v235, 3
	v_readlane_b32 s39, v235, 4
	v_readlane_b32 s40, v235, 5
	v_readlane_b32 s41, v235, 6
	v_readlane_b32 s42, v235, 7
	v_readlane_b32 s43, v235, 8
	v_readlane_b32 s44, v235, 9
	v_readlane_b32 s45, v235, 10
	v_readlane_b32 s48, v235, 13
	v_readlane_b32 s49, v235, 14
	v_readlane_b32 s50, v235, 15
	v_readlane_b32 s51, v235, 16
	s_and_saveexec_b64 s[0:1], vcc
	s_cbranch_execz .LBB0_478
	v_lshlrev_b64 v[0:1], 13, v[204:205]
	v_lshl_add_u64 v[0:1], v[206:207], 0, v[0:1]
	global_load_dwordx4 v[0:3], v[0:1], off nt

.LBB0_485:
	v_lshlrev_b64 v[0:1], 13, v[204:205]
	v_lshl_add_u64 v[0:1], v[206:207], 0, v[0:1]
	v_add_co_u32_e32 v0, vcc, 0x70000, v0
	s_nop 1
	v_addc_co_u32_e32 v1, vcc, 0, v1, vcc
	global_load_dwordx4 v[124:127], v[0:1], off nt
	s_waitcnt vmcnt(0)
	v_mov_b64_e32 v[0:1], v[96:97]
	v_mov_b64_e32 v[2:3], v[98:99]
	v_mov_b64_e32 v[4:5], v[100:101]
	v_mov_b64_e32 v[6:7], v[102:103]
	v_mov_b64_e32 v[8:9], v[104:105]
	v_mov_b64_e32 v[10:11], v[106:107]
	v_mov_b64_e32 v[12:13], v[108:109]
	v_mov_b64_e32 v[14:15], v[110:111]
	v_mov_b64_e32 v[16:17], v[112:113]
	v_mov_b64_e32 v[18:19], v[114:115]
	v_mov_b64_e32 v[20:21], v[116:117]
	v_mov_b64_e32 v[22:23], v[118:119]
	v_mov_b64_e32 v[24:25], v[120:121]
	v_mov_b64_e32 v[26:27], v[122:123]
	v_mov_b64_e32 v[28:29], v[124:125]
	v_mov_b64_e32 v[30:31], v[126:127]

.LBB0_488:
	s_andn2_b64 vcc, exec, s[0:1]
	s_cbranch_vccnz .LBB0_502
	s_and_b32 s0, s8, 0x7c0
	s_and_b32 s2, s10, 0x7e0
	s_add_i32 s6, s0, 0xfffffc00
	v_or_b32_e32 v0, s2, v209
	v_readlane_b32 s36, v235, 1
	v_add_u32_e32 v204, s6, v210
	v_lshlrev_b32_e32 v192, 2, v0
	v_readlane_b32 s44, v235, 9
	v_readlane_b32 s45, v235, 10
	v_mov_b32_e32 v0, 0
	v_cmp_gt_i32_e32 vcc, s28, v204
	v_lshl_add_u64 v[206:207], s[44:45], 0, v[192:193]
	v_ashrrev_i32_e32 v205, 31, v204
	v_mov_b32_e32 v1, v0
	v_mov_b32_e32 v2, v0
	v_mov_b32_e32 v3, v0
	v_readlane_b32 s37, v235, 2
	v_readlane_b32 s38, v235, 3
	v_readlane_b32 s39, v235, 4
	v_readlane_b32 s40, v235, 5
	v_readlane_b32 s41, v235, 6
	v_readlane_b32 s42, v235, 7
	v_readlane_b32 s43, v235, 8
	v_readlane_b32 s46, v235, 11
	v_readlane_b32 s47, v235, 12
	v_readlane_b32 s48, v235, 13
	v_readlane_b32 s49, v235, 14
	v_readlane_b32 s50, v235, 15
	v_readlane_b32 s51, v235, 16
	s_and_saveexec_b64 s[0:1], vcc
	s_cbranch_execz .LBB0_491
	v_lshlrev_b64 v[0:1], 13, v[204:205]
	v_lshl_add_u64 v[0:1], v[206:207], 0, v[0:1]
	global_load_dwordx4 v[0:3], v[0:1], off nt
.LBB0_491:
	s_or_b64 exec, exec, s[0:1]
	v_mov_b32_e32 v30, s7
	v_mov_b32_e32 v31, s7
	v_mov_b32_e32 v4, s7
	v_mov_b32_e32 v5, s7
	v_mov_b32_e32 v6, s7
	v_mov_b32_e32 v7, s7
	v_mov_b32_e32 v8, s7
	v_mov_b32_e32 v9, s7
	v_mov_b32_e32 v10, s7
	v_mov_b32_e32 v11, s7
	v_mov_b32_e32 v12, s7
	v_mov_b32_e32 v13, s7
	v_mov_b32_e32 v14, s7
	v_mov_b32_e32 v15, s7
	v_mov_b32_e32 v16, s7
	v_mov_b32_e32 v17, s7
	v_mov_b32_e32 v18, s7
	v_mov_b32_e32 v19, s7
	v_mov_b32_e32 v20, s7
	v_mov_b32_e32 v21, s7
	v_mov_b32_e32 v22, s7
	v_mov_b32_e32 v23, s7
	v_mov_b32_e32 v24, s7
	v_mov_b32_e32 v25, s7
	v_mov_b32_e32 v26, s7
	v_mov_b32_e32 v27, s7
	v_mov_b32_e32 v28, s7
	v_mov_b32_e32 v29, s7
	s_movk_i32 s0, 0x3f8
	s_waitcnt vmcnt(0)
	v_mov_b64_e32 v[126:127], v[30:31]
	v_mov_b64_e32 v[62:63], v[30:31]
	v_mov_b64_e32 v[94:95], v[30:31]
	v_mov_b64_e32 v[190:191], v[30:31]
	v_mov_b64_e32 v[158:159], v[30:31]
	v_cmp_gt_i32_e32 vcc, s0, v204
	v_mov_b64_e32 v[122:123], v[26:27]
	v_mov_b64_e32 v[120:121], v[24:25]
	v_mov_b64_e32 v[118:119], v[22:23]
	v_mov_b64_e32 v[116:117], v[20:21]
	v_mov_b64_e32 v[114:115], v[18:19]
	v_mov_b64_e32 v[112:113], v[16:17]
	v_mov_b64_e32 v[110:111], v[14:15]
	v_mov_b64_e32 v[108:109], v[12:13]
	v_mov_b64_e32 v[106:107], v[10:11]
	v_mov_b64_e32 v[104:105], v[8:9]
	v_mov_b64_e32 v[102:103], v[6:7]
	v_mov_b64_e32 v[100:101], v[4:5]
	v_mov_b64_e32 v[98:99], v[2:3]
	v_mov_b64_e32 v[96:97], v[0:1]
	v_mov_b64_e32 v[60:61], v[28:29]
	v_mov_b64_e32 v[54:55], v[22:23]
	v_mov_b64_e32 v[52:53], v[20:21]
	v_mov_b64_e32 v[50:51], v[18:19]
	v_mov_b64_e32 v[48:49], v[16:17]
	v_mov_b64_e32 v[46:47], v[14:15]
	v_mov_b64_e32 v[44:45], v[12:13]
	v_mov_b64_e32 v[42:43], v[10:11]
	v_mov_b64_e32 v[40:41], v[8:9]
	v_mov_b64_e32 v[38:39], v[6:7]
	v_mov_b64_e32 v[36:37], v[4:5]
	v_mov_b64_e32 v[34:35], v[2:3]
	v_mov_b64_e32 v[32:33], v[0:1]
	v_mov_b64_e32 v[92:93], v[28:29]
	v_mov_b64_e32 v[90:91], v[26:27]
	v_mov_b64_e32 v[88:89], v[24:25]
	v_mov_b64_e32 v[82:83], v[18:19]
	v_mov_b64_e32 v[80:81], v[16:17]
	v_mov_b64_e32 v[78:79], v[14:15]
	v_mov_b64_e32 v[76:77], v[12:13]
	v_mov_b64_e32 v[74:75], v[10:11]
	v_mov_b64_e32 v[72:73], v[8:9]
	v_mov_b64_e32 v[70:71], v[6:7]
	v_mov_b64_e32 v[68:69], v[4:5]
	v_mov_b64_e32 v[66:67], v[2:3]
	v_mov_b64_e32 v[64:65], v[0:1]
	v_mov_b64_e32 v[188:189], v[28:29]
	v_mov_b64_e32 v[186:187], v[26:27]
	v_mov_b64_e32 v[184:185], v[24:25]
	v_mov_b64_e32 v[182:183], v[22:23]
	v_mov_b64_e32 v[180:181], v[20:21]
	v_mov_b64_e32 v[174:175], v[14:15]
	v_mov_b64_e32 v[172:173], v[12:13]
	v_mov_b64_e32 v[170:171], v[10:11]
	v_mov_b64_e32 v[168:169], v[8:9]
	v_mov_b64_e32 v[166:167], v[6:7]
	v_mov_b64_e32 v[164:165], v[4:5]
	v_mov_b64_e32 v[162:163], v[2:3]
	v_mov_b64_e32 v[160:161], v[0:1]
	v_mov_b64_e32 v[156:157], v[28:29]
	v_mov_b64_e32 v[154:155], v[26:27]
	v_mov_b64_e32 v[152:153], v[24:25]
	v_mov_b64_e32 v[150:151], v[22:23]
	v_mov_b64_e32 v[148:149], v[20:21]
	v_mov_b64_e32 v[146:147], v[18:19]
	v_mov_b64_e32 v[144:145], v[16:17]
	v_mov_b64_e32 v[142:143], v[14:15]
	v_mov_b64_e32 v[140:141], v[12:13]
	v_mov_b64_e32 v[138:139], v[10:11]
	v_mov_b64_e32 v[136:137], v[8:9]
	v_mov_b64_e32 v[134:135], v[6:7]
	v_mov_b64_e32 v[132:133], v[4:5]
	v_mov_b64_e32 v[130:131], v[2:3]
	v_mov_b64_e32 v[128:129], v[0:1]
	v_mov_b64_e32 v[124:125], v[28:29]
	v_mov_b64_e32 v[58:59], v[26:27]
	v_mov_b64_e32 v[56:57], v[24:25]
	v_mov_b64_e32 v[86:87], v[22:23]
	v_mov_b64_e32 v[84:85], v[20:21]
	v_mov_b64_e32 v[178:179], v[18:19]
	v_mov_b64_e32 v[176:177], v[16:17]
	s_and_saveexec_b64 s[0:1], vcc
	s_cbranch_execz .LBB0_493
	v_lshlrev_b64 v[4:5], 13, v[204:205]
	v_lshl_add_u64 v[4:5], v[206:207], 0, v[4:5]
	v_add_co_u32_e32 v4, vcc, 0x10000, v4
	s_nop 1
	v_addc_co_u32_e32 v5, vcc, 0, v5, vcc
	global_load_dwordx4 v[4:7], v[4:5], off nt
	s_waitcnt vmcnt(0)
	v_mov_b64_e32 v[158:159], v[30:31]
	v_mov_b64_e32 v[138:139], v[10:11]
	v_mov_b64_e32 v[136:137], v[8:9]
	v_mov_b64_e32 v[156:157], v[28:29]
	v_mov_b64_e32 v[154:155], v[26:27]
	v_mov_b64_e32 v[152:153], v[24:25]
	v_mov_b64_e32 v[150:151], v[22:23]
	v_mov_b64_e32 v[148:149], v[20:21]
	v_mov_b64_e32 v[146:147], v[18:19]
	v_mov_b64_e32 v[144:145], v[16:17]
	v_mov_b64_e32 v[142:143], v[14:15]
	v_mov_b64_e32 v[140:141], v[12:13]
	v_mov_b64_e32 v[130:131], v[2:3]
	v_mov_b64_e32 v[128:129], v[0:1]
	v_mov_b32_e32 v136, s7
	v_mov_b32_e32 v137, s7
	v_mov_b32_e32 v138, s7
	v_mov_b32_e32 v139, s7
	v_mov_b64_e32 v[134:135], v[6:7]
	v_mov_b64_e32 v[132:133], v[4:5]
	v_mov_b64_e32 v[190:191], v[158:159]
	v_mov_b64_e32 v[174:175], v[142:143]
	v_mov_b64_e32 v[172:173], v[140:141]
	v_mov_b64_e32 v[160:161], v[128:129]
	v_mov_b64_e32 v[188:189], v[156:157]
	v_mov_b64_e32 v[186:187], v[154:155]
	v_mov_b64_e32 v[184:185], v[152:153]
	v_mov_b64_e32 v[182:183], v[150:151]
	v_mov_b64_e32 v[180:181], v[148:149]
	v_mov_b64_e32 v[178:179], v[146:147]
	v_mov_b64_e32 v[176:177], v[144:145]
	v_mov_b64_e32 v[170:171], v[138:139]
	v_mov_b64_e32 v[168:169], v[136:137]
	v_mov_b64_e32 v[166:167], v[134:135]
	v_mov_b64_e32 v[164:165], v[132:133]
	v_mov_b64_e32 v[162:163], v[130:131]
	v_mov_b32_e32 v172, s7
	v_mov_b32_e32 v173, s7
	v_mov_b32_e32 v174, s7
	v_mov_b32_e32 v175, s7
	v_mov_b64_e32 v[64:65], v[160:161]
	v_mov_b64_e32 v[80:81], v[176:177]
	v_mov_b64_e32 v[82:83], v[178:179]
	v_mov_b64_e32 v[66:67], v[162:163]
	v_mov_b64_e32 v[68:69], v[164:165]
	v_mov_b64_e32 v[70:71], v[166:167]
	v_mov_b64_e32 v[72:73], v[168:169]
	v_mov_b64_e32 v[74:75], v[170:171]
	v_mov_b64_e32 v[76:77], v[172:173]
	v_mov_b64_e32 v[78:79], v[174:175]
	v_mov_b64_e32 v[84:85], v[180:181]
	v_mov_b64_e32 v[86:87], v[182:183]
	v_mov_b64_e32 v[88:89], v[184:185]
	v_mov_b64_e32 v[90:91], v[186:187]
	v_mov_b64_e32 v[92:93], v[188:189]
	v_mov_b64_e32 v[94:95], v[190:191]
	v_mov_b32_e32 v80, s7
	v_mov_b32_e32 v81, s7
	v_mov_b32_e32 v82, s7
	v_mov_b32_e32 v83, s7
	v_mov_b64_e32 v[32:33], v[64:65]
	v_mov_b64_e32 v[52:53], v[84:85]
	v_mov_b64_e32 v[54:55], v[86:87]
	v_mov_b64_e32 v[62:63], v[94:95]
	v_mov_b64_e32 v[34:35], v[66:67]
	v_mov_b64_e32 v[36:37], v[68:69]
	v_mov_b64_e32 v[38:39], v[70:71]
	v_mov_b64_e32 v[40:41], v[72:73]
	v_mov_b64_e32 v[42:43], v[74:75]
	v_mov_b64_e32 v[44:45], v[76:77]
	v_mov_b64_e32 v[46:47], v[78:79]
	v_mov_b64_e32 v[48:49], v[80:81]
	v_mov_b64_e32 v[50:51], v[82:83]
	v_mov_b64_e32 v[56:57], v[88:89]
	v_mov_b64_e32 v[58:59], v[90:91]
	v_mov_b64_e32 v[60:61], v[92:93]
	v_mov_b32_e32 v52, s7
	v_mov_b32_e32 v53, s7
	v_mov_b32_e32 v54, s7
	v_mov_b32_e32 v55, s7
	v_mov_b64_e32 v[126:127], v[62:63]
	v_mov_b64_e32 v[122:123], v[58:59]
	v_mov_b64_e32 v[120:121], v[56:57]
	v_mov_b64_e32 v[96:97], v[32:33]
	v_mov_b64_e32 v[124:125], v[60:61]
	v_mov_b64_e32 v[118:119], v[54:55]
	v_mov_b64_e32 v[116:117], v[52:53]
	v_mov_b64_e32 v[114:115], v[50:51]
	v_mov_b64_e32 v[112:113], v[48:49]
	v_mov_b64_e32 v[110:111], v[46:47]
	v_mov_b64_e32 v[108:109], v[44:45]
	v_mov_b64_e32 v[106:107], v[42:43]
	v_mov_b64_e32 v[104:105], v[40:41]
	v_mov_b64_e32 v[102:103], v[38:39]
	v_mov_b64_e32 v[100:101], v[36:37]
	v_mov_b64_e32 v[98:99], v[34:35]
	v_mov_b32_e32 v120, s7
	v_mov_b32_e32 v121, s7
	v_mov_b32_e32 v122, s7
	v_mov_b32_e32 v123, s7
	v_mov_b64_e32 v[0:1], v[96:97]
	v_mov_b64_e32 v[28:29], v[124:125]
	v_mov_b64_e32 v[30:31], v[126:127]
	v_mov_b64_e32 v[2:3], v[98:99]
	v_mov_b64_e32 v[4:5], v[100:101]
	v_mov_b64_e32 v[6:7], v[102:103]
	v_mov_b64_e32 v[8:9], v[104:105]
	v_mov_b64_e32 v[10:11], v[106:107]
	v_mov_b64_e32 v[12:13], v[108:109]
	v_mov_b64_e32 v[14:15], v[110:111]
	v_mov_b64_e32 v[16:17], v[112:113]
	v_mov_b64_e32 v[18:19], v[114:115]
	v_mov_b64_e32 v[20:21], v[116:117]
	v_mov_b64_e32 v[22:23], v[118:119]
	v_mov_b64_e32 v[24:25], v[120:121]
	v_mov_b64_e32 v[26:27], v[122:123]
	v_mov_b32_e32 v28, s7
	v_mov_b32_e32 v29, s7
	v_mov_b32_e32 v30, s7
	v_mov_b32_e32 v31, s7
.LBB0_493:
	s_or_b64 exec, exec, s[0:1]
	s_movk_i32 s0, 0x3f0
	v_cmp_gt_i32_e32 vcc, s0, v204
	s_and_saveexec_b64 s[0:1], vcc
	s_cbranch_execz .LBB0_495
	v_lshlrev_b64 v[0:1], 13, v[204:205]
	v_lshl_add_u64 v[0:1], v[206:207], 0, v[0:1]
	v_add_co_u32_e32 v0, vcc, 0x20000, v0
	s_nop 1
	v_addc_co_u32_e32 v1, vcc, 0, v1, vcc
	global_load_dwordx4 v[136:139], v[0:1], off nt
	s_waitcnt vmcnt(0)
	v_mov_b64_e32 v[190:191], v[158:159]
	v_mov_b64_e32 v[174:175], v[142:143]
	v_mov_b64_e32 v[172:173], v[140:141]
	v_mov_b64_e32 v[160:161], v[128:129]
	v_mov_b64_e32 v[188:189], v[156:157]
	v_mov_b64_e32 v[186:187], v[154:155]
	v_mov_b64_e32 v[184:185], v[152:153]
	v_mov_b64_e32 v[182:183], v[150:151]
	v_mov_b64_e32 v[180:181], v[148:149]
	v_mov_b64_e32 v[178:179], v[146:147]
	v_mov_b64_e32 v[176:177], v[144:145]
	v_mov_b64_e32 v[166:167], v[134:135]
	v_mov_b64_e32 v[164:165], v[132:133]
	v_mov_b64_e32 v[162:163], v[130:131]
	v_mov_b32_e32 v172, s7
	v_mov_b32_e32 v173, s7
	v_mov_b32_e32 v174, s7
	v_mov_b32_e32 v175, s7
	v_mov_b64_e32 v[170:171], v[138:139]
	v_mov_b64_e32 v[168:169], v[136:137]
	v_mov_b64_e32 v[64:65], v[160:161]
	v_mov_b64_e32 v[80:81], v[176:177]
	v_mov_b64_e32 v[82:83], v[178:179]
	v_mov_b64_e32 v[66:67], v[162:163]
	v_mov_b64_e32 v[68:69], v[164:165]
	v_mov_b64_e32 v[70:71], v[166:167]
	v_mov_b64_e32 v[72:73], v[168:169]
	v_mov_b64_e32 v[74:75], v[170:171]
	v_mov_b64_e32 v[76:77], v[172:173]
	v_mov_b64_e32 v[78:79], v[174:175]
	v_mov_b64_e32 v[84:85], v[180:181]
	v_mov_b64_e32 v[86:87], v[182:183]
	v_mov_b64_e32 v[88:89], v[184:185]
	v_mov_b64_e32 v[90:91], v[186:187]
	v_mov_b64_e32 v[92:93], v[188:189]
	v_mov_b64_e32 v[94:95], v[190:191]
	v_mov_b32_e32 v80, s7
	v_mov_b32_e32 v81, s7
	v_mov_b32_e32 v82, s7
	v_mov_b32_e32 v83, s7
	v_mov_b64_e32 v[32:33], v[64:65]
	v_mov_b64_e32 v[52:53], v[84:85]
	v_mov_b64_e32 v[54:55], v[86:87]
	v_mov_b64_e32 v[62:63], v[94:95]
	v_mov_b64_e32 v[34:35], v[66:67]
	v_mov_b64_e32 v[36:37], v[68:69]
	v_mov_b64_e32 v[38:39], v[70:71]
	v_mov_b64_e32 v[40:41], v[72:73]
	v_mov_b64_e32 v[42:43], v[74:75]
	v_mov_b64_e32 v[44:45], v[76:77]
	v_mov_b64_e32 v[46:47], v[78:79]
	v_mov_b64_e32 v[48:49], v[80:81]
	v_mov_b64_e32 v[50:51], v[82:83]
	v_mov_b64_e32 v[56:57], v[88:89]
	v_mov_b64_e32 v[58:59], v[90:91]
	v_mov_b64_e32 v[60:61], v[92:93]
	v_mov_b32_e32 v52, s7
	v_mov_b32_e32 v53, s7
	v_mov_b32_e32 v54, s7
	v_mov_b32_e32 v55, s7
	v_mov_b64_e32 v[126:127], v[62:63]
	v_mov_b64_e32 v[122:123], v[58:59]
	v_mov_b64_e32 v[120:121], v[56:57]
	v_mov_b64_e32 v[96:97], v[32:33]
	v_mov_b64_e32 v[124:125], v[60:61]
	v_mov_b64_e32 v[118:119], v[54:55]
	v_mov_b64_e32 v[116:117], v[52:53]
	v_mov_b64_e32 v[114:115], v[50:51]
	v_mov_b64_e32 v[112:113], v[48:49]
	v_mov_b64_e32 v[110:111], v[46:47]
	v_mov_b64_e32 v[108:109], v[44:45]
	v_mov_b64_e32 v[106:107], v[42:43]
	v_mov_b64_e32 v[104:105], v[40:41]
	v_mov_b64_e32 v[102:103], v[38:39]
	v_mov_b64_e32 v[100:101], v[36:37]
	v_mov_b64_e32 v[98:99], v[34:35]
	v_mov_b32_e32 v120, s7
	v_mov_b32_e32 v121, s7
	v_mov_b32_e32 v122, s7
	v_mov_b32_e32 v123, s7
	v_mov_b64_e32 v[0:1], v[96:97]
	v_mov_b64_e32 v[28:29], v[124:125]
	v_mov_b64_e32 v[30:31], v[126:127]
	v_mov_b64_e32 v[2:3], v[98:99]
	v_mov_b64_e32 v[4:5], v[100:101]
	v_mov_b64_e32 v[6:7], v[102:103]
	v_mov_b64_e32 v[8:9], v[104:105]
	v_mov_b64_e32 v[10:11], v[106:107]
	v_mov_b64_e32 v[12:13], v[108:109]
	v_mov_b64_e32 v[14:15], v[110:111]
	v_mov_b64_e32 v[16:17], v[112:113]
	v_mov_b64_e32 v[18:19], v[114:115]
	v_mov_b64_e32 v[20:21], v[116:117]
	v_mov_b64_e32 v[22:23], v[118:119]
	v_mov_b64_e32 v[24:25], v[120:121]
	v_mov_b64_e32 v[26:27], v[122:123]
	v_mov_b32_e32 v28, s7
	v_mov_b32_e32 v29, s7
	v_mov_b32_e32 v30, s7
	v_mov_b32_e32 v31, s7

.LBB0_503:
	s_ashr_i32 s0, s8, 31
	s_lshr_b32 s0, s0, 26
	s_add_i32 s1, s8, s0
	s_and_b32 s0, s1, 0xffffffc0
	s_lshl_b32 s1, s1, 5
	s_and_b32 s1, s1, 0xfffff800
	s_sub_i32 s2, s8, s0
	s_sub_i32 s3, s10, s1
	s_cmp_gt_i32 s2, -1
	v_add_u32_e32 v160, s0, v210
	v_readlane_b32 s36, v235, 1
	v_add_u32_e32 v192, s3, v209
	s_cselect_b64 s[2:3], -1, 0
	v_readlane_b32 s42, v235, 7
	v_readlane_b32 s43, v235, 8
	v_cmp_gt_i32_e32 vcc, s28, v160
	v_mov_b32_e32 v0, 0
	v_lshl_add_u64 v[162:163], v[192:193], 2, s[42:43]
	s_and_b64 s[34:35], s[2:3], vcc
	v_mov_b32_e32 v1, v0
	v_mov_b32_e32 v2, v0
	v_mov_b32_e32 v3, v0
	v_readlane_b32 s37, v235, 2
	v_readlane_b32 s38, v235, 3
	v_readlane_b32 s39, v235, 4
	v_readlane_b32 s40, v235, 5
	v_readlane_b32 s41, v235, 6
	v_readlane_b32 s44, v235, 9
	v_readlane_b32 s45, v235, 10
	v_readlane_b32 s46, v235, 11
	v_readlane_b32 s47, v235, 12
	v_readlane_b32 s48, v235, 13
	v_readlane_b32 s49, v235, 14
	v_readlane_b32 s50, v235, 15
	v_readlane_b32 s51, v235, 16
	s_and_saveexec_b64 s[4:5], s[34:35]
	s_cbranch_execz .LBB0_505
	v_ashrrev_i32_e32 v161, 31, v160
	v_lshlrev_b64 v[0:1], 13, v[160:161]
	v_lshl_add_u64 v[0:1], v[162:163], 0, v[0:1]
	global_load_dwordx4 v[0:3], v[0:1], off nt
.LBB0_505:
	s_or_b64 exec, exec, s[4:5]
	v_mov_b32_e32 v4, s7
	v_mov_b32_e32 v5, s7
	v_mov_b32_e32 v6, s7
	v_mov_b32_e32 v7, s7
	v_mov_b32_e32 v8, s7
	v_mov_b32_e32 v9, s7
	v_mov_b32_e32 v10, s7
	v_mov_b32_e32 v11, s7
	v_mov_b32_e32 v12, s7
	v_mov_b32_e32 v13, s7
	v_mov_b32_e32 v14, s7
	v_mov_b32_e32 v15, s7
	s_waitcnt vmcnt(0)
	v_mov_b64_e32 v[158:159], v[30:31]
	v_mov_b64_e32 v[146:147], v[18:19]
	v_mov_b64_e32 v[144:145], v[16:17]
	v_mov_b64_e32 v[128:129], v[0:1]
	v_mov_b64_e32 v[156:157], v[28:29]
	v_mov_b64_e32 v[154:155], v[26:27]
	v_mov_b64_e32 v[152:153], v[24:25]
	v_mov_b64_e32 v[150:151], v[22:23]
	v_mov_b64_e32 v[148:149], v[20:21]
	v_mov_b64_e32 v[142:143], v[14:15]
	v_mov_b64_e32 v[140:141], v[12:13]
	v_mov_b64_e32 v[138:139], v[10:11]
	v_mov_b64_e32 v[136:137], v[8:9]
	v_mov_b64_e32 v[134:135], v[6:7]
	v_mov_b64_e32 v[132:133], v[4:5]
	v_mov_b64_e32 v[130:131], v[2:3]
	v_mov_b32_e32 v144, s7
	v_mov_b32_e32 v145, s7
	v_mov_b32_e32 v146, s7
	v_mov_b32_e32 v147, s7
	v_mov_b64_e32 v[64:65], v[128:129]
	v_mov_b64_e32 v[84:85], v[148:149]
	v_mov_b64_e32 v[86:87], v[150:151]
	v_mov_b64_e32 v[66:67], v[130:131]
	v_mov_b64_e32 v[68:69], v[132:133]
	v_mov_b64_e32 v[70:71], v[134:135]
	v_mov_b64_e32 v[72:73], v[136:137]
	v_mov_b64_e32 v[74:75], v[138:139]
	v_mov_b64_e32 v[76:77], v[140:141]
	v_mov_b64_e32 v[78:79], v[142:143]
	v_mov_b64_e32 v[80:81], v[144:145]
	v_mov_b64_e32 v[82:83], v[146:147]
	v_mov_b64_e32 v[88:89], v[152:153]
	v_mov_b64_e32 v[90:91], v[154:155]
	v_mov_b64_e32 v[92:93], v[156:157]
	v_mov_b64_e32 v[94:95], v[158:159]
	v_mov_b32_e32 v84, s7
	v_mov_b32_e32 v85, s7
	v_mov_b32_e32 v86, s7
	v_mov_b32_e32 v87, s7
	v_mov_b64_e32 v[32:33], v[64:65]
	v_mov_b64_e32 v[56:57], v[88:89]
	v_mov_b64_e32 v[58:59], v[90:91]
	v_mov_b64_e32 v[62:63], v[94:95]
	v_mov_b64_e32 v[34:35], v[66:67]
	v_mov_b64_e32 v[36:37], v[68:69]
	v_mov_b64_e32 v[38:39], v[70:71]
	v_mov_b64_e32 v[40:41], v[72:73]
	v_mov_b64_e32 v[42:43], v[74:75]
	v_mov_b64_e32 v[44:45], v[76:77]
	v_mov_b64_e32 v[46:47], v[78:79]
	v_mov_b64_e32 v[48:49], v[80:81]
	v_mov_b64_e32 v[50:51], v[82:83]
	v_mov_b64_e32 v[52:53], v[84:85]
	v_mov_b64_e32 v[54:55], v[86:87]
	v_mov_b64_e32 v[60:61], v[92:93]
	v_mov_b32_e32 v56, s7
	v_mov_b32_e32 v57, s7
	v_mov_b32_e32 v58, s7
	v_mov_b32_e32 v59, s7
	v_mov_b64_e32 v[126:127], v[62:63]
	v_mov_b64_e32 v[124:125], v[60:61]
	v_cndmask_b32_e64 v16, 0, 1, s[2:3]
	v_mov_b64_e32 v[122:123], v[58:59]
	v_mov_b64_e32 v[120:121], v[56:57]
	v_mov_b64_e32 v[118:119], v[54:55]
	v_mov_b64_e32 v[116:117], v[52:53]
	v_mov_b64_e32 v[114:115], v[50:51]
	v_mov_b64_e32 v[112:113], v[48:49]
	v_mov_b64_e32 v[110:111], v[46:47]
	v_mov_b64_e32 v[108:109], v[44:45]
	v_mov_b64_e32 v[106:107], v[42:43]
	v_mov_b64_e32 v[104:105], v[40:41]
	v_mov_b64_e32 v[102:103], v[38:39]
	v_mov_b64_e32 v[100:101], v[36:37]
	v_mov_b64_e32 v[98:99], v[34:35]
	v_mov_b64_e32 v[96:97], v[32:33]
	v_mov_b32_e32 v124, s7
	v_mov_b32_e32 v125, s7
	v_mov_b32_e32 v126, s7
	v_cmp_ne_u32_e64 s[4:5], 1, v16
	s_andn2_b64 vcc, exec, s[2:3]
	v_mov_b32_e32 v127, s7
	s_cbranch_vccnz .LBB0_509
	v_add_u32_e32 v16, 8, v160
	v_cmp_gt_i32_e32 vcc, s28, v16
	s_and_saveexec_b64 s[2:3], vcc
	s_cbranch_execz .LBB0_508
	v_ashrrev_i32_e32 v17, 31, v16
	v_lshlrev_b64 v[4:5], 13, v[16:17]
	v_lshl_add_u64 v[4:5], v[162:163], 0, v[4:5]
	global_load_dwordx4 v[4:7], v[4:5], off nt
	v_mov_b32_e32 v30, s7
	v_mov_b32_e32 v31, s7
	v_mov_b32_e32 v8, s7
	v_mov_b32_e32 v9, s7
	v_mov_b32_e32 v10, s7
	v_mov_b32_e32 v11, s7
	v_mov_b32_e32 v12, s7
	v_mov_b32_e32 v13, s7
	v_mov_b32_e32 v14, s7
	v_mov_b32_e32 v15, s7
	v_mov_b32_e32 v16, s7
	v_mov_b32_e32 v17, s7
	v_mov_b32_e32 v18, s7
	v_mov_b32_e32 v19, s7
	v_mov_b32_e32 v20, s7
	v_mov_b32_e32 v21, s7
	v_mov_b32_e32 v22, s7
	v_mov_b32_e32 v23, s7
	v_mov_b32_e32 v24, s7
	v_mov_b32_e32 v25, s7
	v_mov_b32_e32 v26, s7
	v_mov_b32_e32 v27, s7
	v_mov_b32_e32 v28, s7
	v_mov_b32_e32 v29, s7
	s_waitcnt vmcnt(0)
	v_mov_b64_e32 v[158:159], v[30:31]
	v_mov_b64_e32 v[94:95], v[30:31]
	v_mov_b64_e32 v[62:63], v[30:31]
	v_mov_b64_e32 v[126:127], v[30:31]
	v_mov_b64_e32 v[156:157], v[28:29]
	v_mov_b64_e32 v[154:155], v[26:27]
	v_mov_b64_e32 v[152:153], v[24:25]
	v_mov_b64_e32 v[146:147], v[18:19]
	v_mov_b64_e32 v[144:145], v[16:17]
	v_mov_b64_e32 v[142:143], v[14:15]
	v_mov_b64_e32 v[140:141], v[12:13]
	v_mov_b64_e32 v[138:139], v[10:11]
	v_mov_b64_e32 v[136:137], v[8:9]
	v_mov_b64_e32 v[130:131], v[2:3]
	v_mov_b64_e32 v[128:129], v[0:1]
	v_mov_b64_e32 v[92:93], v[28:29]
	v_mov_b64_e32 v[86:87], v[22:23]
	v_mov_b64_e32 v[84:85], v[20:21]
	v_mov_b64_e32 v[82:83], v[18:19]
	v_mov_b64_e32 v[80:81], v[16:17]
	v_mov_b64_e32 v[78:79], v[14:15]
	v_mov_b64_e32 v[76:77], v[12:13]
	v_mov_b64_e32 v[74:75], v[10:11]
	v_mov_b64_e32 v[72:73], v[8:9]
	v_mov_b64_e32 v[66:67], v[2:3]
	v_mov_b64_e32 v[64:65], v[0:1]
	v_mov_b64_e32 v[58:59], v[26:27]
	v_mov_b64_e32 v[56:57], v[24:25]
	v_mov_b64_e32 v[54:55], v[22:23]
	v_mov_b64_e32 v[52:53], v[20:21]
	v_mov_b64_e32 v[50:51], v[18:19]
	v_mov_b64_e32 v[48:49], v[16:17]
	v_mov_b64_e32 v[46:47], v[14:15]
	v_mov_b64_e32 v[44:45], v[12:13]
	v_mov_b64_e32 v[42:43], v[10:11]
	v_mov_b64_e32 v[40:41], v[8:9]
	v_mov_b64_e32 v[34:35], v[2:3]
	v_mov_b64_e32 v[32:33], v[0:1]
	v_mov_b64_e32 v[124:125], v[28:29]
	v_mov_b64_e32 v[122:123], v[26:27]
	v_mov_b64_e32 v[120:121], v[24:25]
	v_mov_b64_e32 v[118:119], v[22:23]
	v_mov_b64_e32 v[116:117], v[20:21]
	v_mov_b64_e32 v[114:115], v[18:19]
	v_mov_b64_e32 v[112:113], v[16:17]
	v_mov_b64_e32 v[110:111], v[14:15]
	v_mov_b64_e32 v[108:109], v[12:13]
	v_mov_b64_e32 v[106:107], v[10:11]
	v_mov_b64_e32 v[104:105], v[8:9]
	v_mov_b64_e32 v[98:99], v[2:3]
	v_mov_b64_e32 v[96:97], v[0:1]
	v_mov_b64_e32 v[150:151], v[22:23]
	v_mov_b64_e32 v[148:149], v[20:21]
	v_mov_b64_e32 v[90:91], v[26:27]
	v_mov_b64_e32 v[88:89], v[24:25]
	v_mov_b64_e32 v[134:135], v[6:7]
	v_mov_b64_e32 v[132:133], v[4:5]
	v_mov_b64_e32 v[70:71], v[6:7]
	v_mov_b64_e32 v[68:69], v[4:5]
	v_mov_b64_e32 v[38:39], v[6:7]
	v_mov_b64_e32 v[36:37], v[4:5]
	v_mov_b64_e32 v[102:103], v[6:7]
	v_mov_b64_e32 v[100:101], v[4:5]
	v_mov_b64_e32 v[60:61], v[28:29]

.LBB0_509:
	s_and_b64 vcc, exec, s[4:5]
	s_cbranch_vccnz .LBB0_513
	v_add_u32_e32 v60, 16, v160
	v_cmp_gt_i32_e32 vcc, s28, v60
	s_and_saveexec_b64 s[2:3], vcc
	s_cbranch_execz .LBB0_512
	v_ashrrev_i32_e32 v61, 31, v60
	v_lshlrev_b64 v[8:9], 13, v[60:61]
	v_lshl_add_u64 v[8:9], v[162:163], 0, v[8:9]
	global_load_dwordx4 v[8:11], v[8:9], off nt
	v_mov_b32_e32 v12, s7
	v_mov_b32_e32 v13, s7
	v_mov_b32_e32 v14, s7
	v_mov_b32_e32 v15, s7
	s_waitcnt vmcnt(0)
	v_mov_b64_e32 v[158:159], v[30:31]
	v_mov_b64_e32 v[146:147], v[18:19]
	v_mov_b64_e32 v[144:145], v[16:17]
	v_mov_b64_e32 v[128:129], v[0:1]
	v_mov_b64_e32 v[156:157], v[28:29]
	v_mov_b64_e32 v[154:155], v[26:27]
	v_mov_b64_e32 v[152:153], v[24:25]
	v_mov_b64_e32 v[150:151], v[22:23]
	v_mov_b64_e32 v[148:149], v[20:21]
	v_mov_b64_e32 v[142:143], v[14:15]
	v_mov_b64_e32 v[140:141], v[12:13]
	v_mov_b64_e32 v[134:135], v[6:7]
	v_mov_b64_e32 v[132:133], v[4:5]
	v_mov_b64_e32 v[130:131], v[2:3]
	v_mov_b32_e32 v144, s7
	v_mov_b32_e32 v145, s7
	v_mov_b32_e32 v146, s7
	v_mov_b32_e32 v147, s7
	v_mov_b64_e32 v[138:139], v[10:11]
	v_mov_b64_e32 v[136:137], v[8:9]
	v_mov_b64_e32 v[64:65], v[128:129]
	v_mov_b64_e32 v[84:85], v[148:149]
	v_mov_b64_e32 v[86:87], v[150:151]
	v_mov_b64_e32 v[66:67], v[130:131]
	v_mov_b64_e32 v[68:69], v[132:133]
	v_mov_b64_e32 v[70:71], v[134:135]
	v_mov_b64_e32 v[72:73], v[136:137]
	v_mov_b64_e32 v[74:75], v[138:139]
	v_mov_b64_e32 v[76:77], v[140:141]
	v_mov_b64_e32 v[78:79], v[142:143]
	v_mov_b64_e32 v[80:81], v[144:145]
	v_mov_b64_e32 v[82:83], v[146:147]
	v_mov_b64_e32 v[88:89], v[152:153]
	v_mov_b64_e32 v[90:91], v[154:155]
	v_mov_b64_e32 v[92:93], v[156:157]
	v_mov_b64_e32 v[94:95], v[158:159]
	v_mov_b32_e32 v84, s7
	v_mov_b32_e32 v85, s7
	v_mov_b32_e32 v86, s7
	v_mov_b32_e32 v87, s7
	v_mov_b64_e32 v[32:33], v[64:65]
	v_mov_b64_e32 v[56:57], v[88:89]
	v_mov_b64_e32 v[58:59], v[90:91]
	v_mov_b64_e32 v[62:63], v[94:95]
	v_mov_b64_e32 v[34:35], v[66:67]
	v_mov_b64_e32 v[36:37], v[68:69]
	v_mov_b64_e32 v[38:39], v[70:71]
	v_mov_b64_e32 v[40:41], v[72:73]
	v_mov_b64_e32 v[42:43], v[74:75]
	v_mov_b64_e32 v[44:45], v[76:77]
	v_mov_b64_e32 v[46:47], v[78:79]
	v_mov_b64_e32 v[48:49], v[80:81]
	v_mov_b64_e32 v[50:51], v[82:83]
	v_mov_b64_e32 v[52:53], v[84:85]
	v_mov_b64_e32 v[54:55], v[86:87]
	v_mov_b64_e32 v[60:61], v[92:93]
	v_mov_b32_e32 v56, s7
	v_mov_b32_e32 v57, s7
	v_mov_b32_e32 v58, s7
	v_mov_b32_e32 v59, s7
	v_mov_b64_e32 v[126:127], v[62:63]
	v_mov_b64_e32 v[124:125], v[60:61]
	v_mov_b64_e32 v[122:123], v[58:59]
	v_mov_b64_e32 v[120:121], v[56:57]
	v_mov_b64_e32 v[118:119], v[54:55]
	v_mov_b64_e32 v[116:117], v[52:53]
	v_mov_b64_e32 v[114:115], v[50:51]
	v_mov_b64_e32 v[112:113], v[48:49]
	v_mov_b64_e32 v[110:111], v[46:47]
	v_mov_b64_e32 v[108:109], v[44:45]
	v_mov_b64_e32 v[106:107], v[42:43]
	v_mov_b64_e32 v[104:105], v[40:41]
	v_mov_b64_e32 v[102:103], v[38:39]
	v_mov_b64_e32 v[100:101], v[36:37]
	v_mov_b64_e32 v[98:99], v[34:35]
	v_mov_b64_e32 v[96:97], v[32:33]
	v_mov_b32_e32 v124, s7
	v_mov_b32_e32 v125, s7
	v_mov_b32_e32 v126, s7
	v_mov_b32_e32 v127, s7

.LBB0_513:
	s_and_b64 vcc, exec, s[4:5]
	s_cbranch_vccnz .LBB0_517
	v_add_u32_e32 v60, 24, v160
	v_cmp_gt_i32_e32 vcc, s28, v60
	s_and_saveexec_b64 s[2:3], vcc
	s_cbranch_execz .LBB0_516
	v_ashrrev_i32_e32 v61, 31, v60
	v_lshlrev_b64 v[12:13], 13, v[60:61]
	v_lshl_add_u64 v[12:13], v[162:163], 0, v[12:13]
	global_load_dwordx4 v[12:15], v[12:13], off nt
	s_waitcnt vmcnt(0)
	v_mov_b64_e32 v[158:159], v[30:31]
	v_mov_b64_e32 v[146:147], v[18:19]
	v_mov_b64_e32 v[144:145], v[16:17]
	v_mov_b64_e32 v[128:129], v[0:1]
	v_mov_b64_e32 v[156:157], v[28:29]
	v_mov_b64_e32 v[154:155], v[26:27]
	v_mov_b64_e32 v[152:153], v[24:25]
	v_mov_b64_e32 v[150:151], v[22:23]
	v_mov_b64_e32 v[148:149], v[20:21]
	v_mov_b64_e32 v[138:139], v[10:11]
	v_mov_b64_e32 v[136:137], v[8:9]
	v_mov_b64_e32 v[134:135], v[6:7]
	v_mov_b64_e32 v[132:133], v[4:5]
	v_mov_b64_e32 v[130:131], v[2:3]
	v_mov_b32_e32 v144, s7
	v_mov_b32_e32 v145, s7
	v_mov_b32_e32 v146, s7
	v_mov_b32_e32 v147, s7
	v_mov_b64_e32 v[142:143], v[14:15]
	v_mov_b64_e32 v[140:141], v[12:13]
	v_mov_b64_e32 v[64:65], v[128:129]
	v_mov_b64_e32 v[84:85], v[148:149]
	v_mov_b64_e32 v[86:87], v[150:151]
	v_mov_b64_e32 v[66:67], v[130:131]
	v_mov_b64_e32 v[68:69], v[132:133]
	v_mov_b64_e32 v[70:71], v[134:135]
	v_mov_b64_e32 v[72:73], v[136:137]
	v_mov_b64_e32 v[74:75], v[138:139]
	v_mov_b64_e32 v[76:77], v[140:141]
	v_mov_b64_e32 v[78:79], v[142:143]
	v_mov_b64_e32 v[80:81], v[144:145]
	v_mov_b64_e32 v[82:83], v[146:147]
	v_mov_b64_e32 v[88:89], v[152:153]
	v_mov_b64_e32 v[90:91], v[154:155]
	v_mov_b64_e32 v[92:93], v[156:157]
	v_mov_b64_e32 v[94:95], v[158:159]
	v_mov_b32_e32 v84, s7
	v_mov_b32_e32 v85, s7
	v_mov_b32_e32 v86, s7
	v_mov_b32_e32 v87, s7
	v_mov_b64_e32 v[32:33], v[64:65]
	v_mov_b64_e32 v[56:57], v[88:89]
	v_mov_b64_e32 v[58:59], v[90:91]
	v_mov_b64_e32 v[62:63], v[94:95]
	v_mov_b64_e32 v[34:35], v[66:67]
	v_mov_b64_e32 v[36:37], v[68:69]
	v_mov_b64_e32 v[38:39], v[70:71]
	v_mov_b64_e32 v[40:41], v[72:73]
	v_mov_b64_e32 v[42:43], v[74:75]
	v_mov_b64_e32 v[44:45], v[76:77]
	v_mov_b64_e32 v[46:47], v[78:79]
	v_mov_b64_e32 v[48:49], v[80:81]
	v_mov_b64_e32 v[50:51], v[82:83]
	v_mov_b64_e32 v[52:53], v[84:85]
	v_mov_b64_e32 v[54:55], v[86:87]
	v_mov_b64_e32 v[60:61], v[92:93]
	v_mov_b32_e32 v56, s7
	v_mov_b32_e32 v57, s7
	v_mov_b32_e32 v58, s7
	v_mov_b32_e32 v59, s7
	v_mov_b64_e32 v[126:127], v[62:63]
	v_mov_b64_e32 v[124:125], v[60:61]
	v_mov_b64_e32 v[122:123], v[58:59]
	v_mov_b64_e32 v[120:121], v[56:57]
	v_mov_b64_e32 v[118:119], v[54:55]
	v_mov_b64_e32 v[116:117], v[52:53]
	v_mov_b64_e32 v[114:115], v[50:51]
	v_mov_b64_e32 v[112:113], v[48:49]
	v_mov_b64_e32 v[110:111], v[46:47]
	v_mov_b64_e32 v[108:109], v[44:45]
	v_mov_b64_e32 v[106:107], v[42:43]
	v_mov_b64_e32 v[104:105], v[40:41]
	v_mov_b64_e32 v[102:103], v[38:39]
	v_mov_b64_e32 v[100:101], v[36:37]
	v_mov_b64_e32 v[98:99], v[34:35]
	v_mov_b64_e32 v[96:97], v[32:33]
	v_mov_b32_e32 v124, s7
	v_mov_b32_e32 v125, s7
	v_mov_b32_e32 v126, s7
	v_mov_b32_e32 v127, s7

.LBB0_517:
	s_and_b64 vcc, exec, s[4:5]
	s_cbranch_vccnz .LBB0_521
	v_add_u32_e32 v16, 32, v160
	v_cmp_gt_i32_e32 vcc, s28, v16
	s_and_saveexec_b64 s[2:3], vcc
	s_cbranch_execz .LBB0_520
	v_ashrrev_i32_e32 v17, 31, v16
	v_lshlrev_b64 v[16:17], 13, v[16:17]
	v_lshl_add_u64 v[16:17], v[162:163], 0, v[16:17]
	global_load_dwordx4 v[16:19], v[16:17], off nt
	s_waitcnt vmcnt(0)
	v_mov_b64_e32 v[94:95], v[30:31]
	v_mov_b64_e32 v[86:87], v[22:23]
	v_mov_b64_e32 v[84:85], v[20:21]
	v_mov_b64_e32 v[64:65], v[0:1]
	v_mov_b64_e32 v[92:93], v[28:29]
	v_mov_b64_e32 v[90:91], v[26:27]
	v_mov_b64_e32 v[88:89], v[24:25]
	v_mov_b64_e32 v[78:79], v[14:15]
	v_mov_b64_e32 v[76:77], v[12:13]
	v_mov_b64_e32 v[74:75], v[10:11]
	v_mov_b64_e32 v[72:73], v[8:9]
	v_mov_b64_e32 v[70:71], v[6:7]
	v_mov_b64_e32 v[68:69], v[4:5]
	v_mov_b64_e32 v[66:67], v[2:3]
	v_mov_b32_e32 v84, s7
	v_mov_b32_e32 v85, s7
	v_mov_b32_e32 v86, s7
	v_mov_b32_e32 v87, s7
	v_mov_b64_e32 v[158:159], v[30:31]
	v_mov_b64_e32 v[156:157], v[28:29]
	v_mov_b64_e32 v[154:155], v[26:27]
	v_mov_b64_e32 v[152:153], v[24:25]
	v_mov_b64_e32 v[142:143], v[14:15]
	v_mov_b64_e32 v[140:141], v[12:13]
	v_mov_b64_e32 v[138:139], v[10:11]
	v_mov_b64_e32 v[136:137], v[8:9]
	v_mov_b64_e32 v[134:135], v[6:7]
	v_mov_b64_e32 v[132:133], v[4:5]
	v_mov_b64_e32 v[130:131], v[2:3]
	v_mov_b64_e32 v[128:129], v[0:1]
	v_mov_b64_e32 v[150:151], v[22:23]
	v_mov_b64_e32 v[148:149], v[20:21]
	v_mov_b64_e32 v[82:83], v[18:19]
	v_mov_b64_e32 v[80:81], v[16:17]
	v_mov_b64_e32 v[32:33], v[64:65]
	v_mov_b64_e32 v[56:57], v[88:89]
	v_mov_b64_e32 v[58:59], v[90:91]
	v_mov_b64_e32 v[62:63], v[94:95]
	v_mov_b64_e32 v[34:35], v[66:67]
	v_mov_b64_e32 v[36:37], v[68:69]
	v_mov_b64_e32 v[38:39], v[70:71]
	v_mov_b64_e32 v[40:41], v[72:73]
	v_mov_b64_e32 v[42:43], v[74:75]
	v_mov_b64_e32 v[44:45], v[76:77]
	v_mov_b64_e32 v[46:47], v[78:79]
	v_mov_b64_e32 v[48:49], v[80:81]
	v_mov_b64_e32 v[50:51], v[82:83]
	v_mov_b64_e32 v[52:53], v[84:85]
	v_mov_b64_e32 v[54:55], v[86:87]
	v_mov_b64_e32 v[60:61], v[92:93]
	v_mov_b32_e32 v56, s7
	v_mov_b32_e32 v57, s7
	v_mov_b32_e32 v58, s7
	v_mov_b32_e32 v59, s7
	v_mov_b64_e32 v[126:127], v[62:63]
	v_mov_b64_e32 v[124:125], v[60:61]
	v_mov_b64_e32 v[122:123], v[58:59]
	v_mov_b64_e32 v[120:121], v[56:57]
	v_mov_b64_e32 v[118:119], v[54:55]
	v_mov_b64_e32 v[116:117], v[52:53]
	v_mov_b64_e32 v[114:115], v[50:51]
	v_mov_b64_e32 v[112:113], v[48:49]
	v_mov_b64_e32 v[110:111], v[46:47]
	v_mov_b64_e32 v[108:109], v[44:45]
	v_mov_b64_e32 v[106:107], v[42:43]
	v_mov_b64_e32 v[104:105], v[40:41]
	v_mov_b64_e32 v[102:103], v[38:39]
	v_mov_b64_e32 v[100:101], v[36:37]
	v_mov_b64_e32 v[98:99], v[34:35]
	v_mov_b64_e32 v[96:97], v[32:33]
	v_mov_b32_e32 v124, s7
	v_mov_b32_e32 v125, s7
	v_mov_b32_e32 v126, s7
	v_mov_b32_e32 v127, s7
	v_mov_b64_e32 v[146:147], v[18:19]
	v_mov_b64_e32 v[144:145], v[16:17]

.LBB0_521:
	s_and_b64 vcc, exec, s[4:5]
	s_cbranch_vccnz .LBB0_525
	v_add_u32_e32 v0, 40, v160
	v_cmp_gt_i32_e32 vcc, s28, v0
	s_and_saveexec_b64 s[2:3], vcc
	s_cbranch_execz .LBB0_524
	v_ashrrev_i32_e32 v1, 31, v0
	v_lshlrev_b64 v[0:1], 13, v[0:1]
	v_lshl_add_u64 v[0:1], v[162:163], 0, v[0:1]
	global_load_dwordx4 v[148:151], v[0:1], off nt
	s_waitcnt vmcnt(0)
	v_mov_b64_e32 v[32:33], v[128:129]
	v_mov_b64_e32 v[56:57], v[152:153]
	v_mov_b64_e32 v[58:59], v[154:155]
	v_mov_b64_e32 v[62:63], v[158:159]
	v_mov_b64_e32 v[34:35], v[130:131]
	v_mov_b64_e32 v[36:37], v[132:133]
	v_mov_b64_e32 v[38:39], v[134:135]
	v_mov_b64_e32 v[40:41], v[136:137]
	v_mov_b64_e32 v[42:43], v[138:139]
	v_mov_b64_e32 v[44:45], v[140:141]
	v_mov_b64_e32 v[46:47], v[142:143]
	v_mov_b64_e32 v[48:49], v[144:145]
	v_mov_b64_e32 v[50:51], v[146:147]
	v_mov_b64_e32 v[60:61], v[156:157]
	v_mov_b32_e32 v56, s7
	v_mov_b32_e32 v57, s7
	v_mov_b32_e32 v58, s7
	v_mov_b32_e32 v59, s7
	v_mov_b64_e32 v[64:65], v[128:129]
	v_mov_b64_e32 v[66:67], v[130:131]
	v_mov_b64_e32 v[68:69], v[132:133]
	v_mov_b64_e32 v[70:71], v[134:135]
	v_mov_b64_e32 v[72:73], v[136:137]
	v_mov_b64_e32 v[74:75], v[138:139]
	v_mov_b64_e32 v[76:77], v[140:141]
	v_mov_b64_e32 v[78:79], v[142:143]
	v_mov_b64_e32 v[80:81], v[144:145]
	v_mov_b64_e32 v[82:83], v[146:147]
	v_mov_b64_e32 v[92:93], v[156:157]
	v_mov_b64_e32 v[94:95], v[158:159]
	v_mov_b64_e32 v[88:89], v[152:153]
	v_mov_b64_e32 v[90:91], v[154:155]
	v_mov_b64_e32 v[52:53], v[148:149]
	v_mov_b64_e32 v[54:55], v[150:151]
	v_mov_b64_e32 v[126:127], v[62:63]
	v_mov_b64_e32 v[124:125], v[60:61]
	v_mov_b64_e32 v[122:123], v[58:59]
	v_mov_b64_e32 v[120:121], v[56:57]
	v_mov_b64_e32 v[118:119], v[54:55]
	v_mov_b64_e32 v[116:117], v[52:53]
	v_mov_b64_e32 v[114:115], v[50:51]
	v_mov_b64_e32 v[112:113], v[48:49]
	v_mov_b64_e32 v[110:111], v[46:47]
	v_mov_b64_e32 v[108:109], v[44:45]
	v_mov_b64_e32 v[106:107], v[42:43]
	v_mov_b64_e32 v[104:105], v[40:41]
	v_mov_b64_e32 v[102:103], v[38:39]
	v_mov_b64_e32 v[100:101], v[36:37]
	v_mov_b64_e32 v[98:99], v[34:35]
	v_mov_b64_e32 v[96:97], v[32:33]
	v_mov_b32_e32 v124, s7
	v_mov_b32_e32 v125, s7
	v_mov_b32_e32 v126, s7
	v_mov_b32_e32 v127, s7
	v_mov_b64_e32 v[84:85], v[148:149]
	v_mov_b64_e32 v[86:87], v[150:151]

.LBB0_525:
	s_and_b64 vcc, exec, s[4:5]
	s_cbranch_vccnz .LBB0_529
	v_add_u32_e32 v0, 48, v160
	v_cmp_gt_i32_e32 vcc, s28, v0
	s_and_saveexec_b64 s[2:3], vcc
	s_cbranch_execz .LBB0_528
	v_ashrrev_i32_e32 v1, 31, v0
	v_lshlrev_b64 v[0:1], 13, v[0:1]
	v_lshl_add_u64 v[0:1], v[162:163], 0, v[0:1]
	global_load_dwordx4 v[88:91], v[0:1], off nt
	s_waitcnt vmcnt(0)
	v_mov_b64_e32 v[126:127], v[94:95]
	v_mov_b64_e32 v[124:125], v[92:93]
	v_mov_b64_e32 v[32:33], v[64:65]
	v_mov_b64_e32 v[118:119], v[86:87]
	v_mov_b64_e32 v[116:117], v[84:85]
	v_mov_b64_e32 v[114:115], v[82:83]
	v_mov_b64_e32 v[112:113], v[80:81]
	v_mov_b64_e32 v[110:111], v[78:79]
	v_mov_b64_e32 v[108:109], v[76:77]
	v_mov_b64_e32 v[106:107], v[74:75]
	v_mov_b64_e32 v[104:105], v[72:73]
	v_mov_b64_e32 v[102:103], v[70:71]
	v_mov_b64_e32 v[100:101], v[68:69]
	v_mov_b64_e32 v[98:99], v[66:67]
	v_mov_b64_e32 v[96:97], v[64:65]
	v_mov_b32_e32 v124, s7
	v_mov_b32_e32 v125, s7
	v_mov_b32_e32 v126, s7
	v_mov_b32_e32 v127, s7
	v_mov_b64_e32 v[34:35], v[66:67]
	v_mov_b64_e32 v[36:37], v[68:69]
	v_mov_b64_e32 v[38:39], v[70:71]
	v_mov_b64_e32 v[40:41], v[72:73]
	v_mov_b64_e32 v[42:43], v[74:75]
	v_mov_b64_e32 v[44:45], v[76:77]
	v_mov_b64_e32 v[46:47], v[78:79]
	v_mov_b64_e32 v[48:49], v[80:81]
	v_mov_b64_e32 v[50:51], v[82:83]
	v_mov_b64_e32 v[52:53], v[84:85]
	v_mov_b64_e32 v[54:55], v[86:87]
	v_mov_b64_e32 v[60:61], v[92:93]
	v_mov_b64_e32 v[62:63], v[94:95]
	v_mov_b64_e32 v[122:123], v[90:91]
	v_mov_b64_e32 v[120:121], v[88:89]
	v_mov_b64_e32 v[56:57], v[88:89]
	v_mov_b64_e32 v[58:59], v[90:91]

.LBB0_529:
	s_and_b64 vcc, exec, s[4:5]
	s_cbranch_vccnz .LBB0_439
	v_add_u32_e32 v0, 56, v160
	v_cmp_gt_i32_e32 vcc, s28, v0
	s_and_saveexec_b64 s[2:3], vcc
	s_cbranch_execz .LBB0_438
	v_ashrrev_i32_e32 v1, 31, v0
	v_lshlrev_b64 v[0:1], 13, v[0:1]
	v_lshl_add_u64 v[0:1], v[162:163], 0, v[0:1]
	global_load_dwordx4 v[60:63], v[0:1], off nt
	s_waitcnt vmcnt(0)
	v_mov_b64_e32 v[126:127], v[62:63]
	v_mov_b64_e32 v[124:125], v[60:61]
	v_mov_b64_e32 v[122:123], v[58:59]
	v_mov_b64_e32 v[120:121], v[56:57]
	v_mov_b64_e32 v[118:119], v[54:55]
	v_mov_b64_e32 v[116:117], v[52:53]
	v_mov_b64_e32 v[114:115], v[50:51]
	v_mov_b64_e32 v[112:113], v[48:49]
	v_mov_b64_e32 v[110:111], v[46:47]
	v_mov_b64_e32 v[108:109], v[44:45]
	v_mov_b64_e32 v[106:107], v[42:43]
	v_mov_b64_e32 v[104:105], v[40:41]
	v_mov_b64_e32 v[102:103], v[38:39]
	v_mov_b64_e32 v[100:101], v[36:37]
	v_mov_b64_e32 v[98:99], v[34:35]
	v_mov_b64_e32 v[96:97], v[32:33]
	s_branch .LBB0_438
.LBB0_532:
	v_lshlrev_b64 v[0:1], 13, v[204:205]
	v_lshl_add_u64 v[0:1], v[206:207], 0, v[0:1]
	v_add_co_u32_e32 v0, vcc, 0x30000, v0
	s_nop 1
	v_addc_co_u32_e32 v1, vcc, 0, v1, vcc
	global_load_dwordx4 v[140:143], v[0:1], off nt
	s_waitcnt vmcnt(0)
	v_mov_b64_e32 v[64:65], v[128:129]
	v_mov_b64_e32 v[80:81], v[144:145]
	v_mov_b64_e32 v[82:83], v[146:147]
	v_mov_b64_e32 v[66:67], v[130:131]
	v_mov_b64_e32 v[68:69], v[132:133]
	v_mov_b64_e32 v[70:71], v[134:135]
	v_mov_b64_e32 v[72:73], v[136:137]
	v_mov_b64_e32 v[74:75], v[138:139]
	v_mov_b64_e32 v[84:85], v[148:149]
	v_mov_b64_e32 v[86:87], v[150:151]
	v_mov_b64_e32 v[88:89], v[152:153]
	v_mov_b64_e32 v[90:91], v[154:155]
	v_mov_b64_e32 v[92:93], v[156:157]
	v_mov_b64_e32 v[94:95], v[158:159]
	v_mov_b32_e32 v80, s7
	v_mov_b32_e32 v81, s7
	v_mov_b32_e32 v82, s7
	v_mov_b32_e32 v83, s7
	v_mov_b64_e32 v[190:191], v[158:159]
	v_mov_b64_e32 v[188:189], v[156:157]
	v_mov_b64_e32 v[186:187], v[154:155]
	v_mov_b64_e32 v[184:185], v[152:153]
	v_mov_b64_e32 v[182:183], v[150:151]
	v_mov_b64_e32 v[180:181], v[148:149]
	v_mov_b64_e32 v[170:171], v[138:139]
	v_mov_b64_e32 v[168:169], v[136:137]
	v_mov_b64_e32 v[166:167], v[134:135]
	v_mov_b64_e32 v[164:165], v[132:133]
	v_mov_b64_e32 v[162:163], v[130:131]
	v_mov_b64_e32 v[160:161], v[128:129]
	v_mov_b64_e32 v[178:179], v[146:147]
	v_mov_b64_e32 v[176:177], v[144:145]
	v_mov_b64_e32 v[76:77], v[140:141]
	v_mov_b64_e32 v[78:79], v[142:143]
	v_mov_b64_e32 v[32:33], v[64:65]
	v_mov_b64_e32 v[52:53], v[84:85]
	v_mov_b64_e32 v[54:55], v[86:87]
	v_mov_b64_e32 v[62:63], v[94:95]
	v_mov_b64_e32 v[34:35], v[66:67]
	v_mov_b64_e32 v[36:37], v[68:69]
	v_mov_b64_e32 v[38:39], v[70:71]
	v_mov_b64_e32 v[40:41], v[72:73]
	v_mov_b64_e32 v[42:43], v[74:75]
	v_mov_b64_e32 v[44:45], v[76:77]
	v_mov_b64_e32 v[46:47], v[78:79]
	v_mov_b64_e32 v[48:49], v[80:81]
	v_mov_b64_e32 v[50:51], v[82:83]
	v_mov_b64_e32 v[56:57], v[88:89]
	v_mov_b64_e32 v[58:59], v[90:91]
	v_mov_b64_e32 v[60:61], v[92:93]
	v_mov_b32_e32 v52, s7
	v_mov_b32_e32 v53, s7
	v_mov_b32_e32 v54, s7
	v_mov_b32_e32 v55, s7
	v_mov_b64_e32 v[126:127], v[62:63]
	v_mov_b64_e32 v[122:123], v[58:59]
	v_mov_b64_e32 v[120:121], v[56:57]
	v_mov_b64_e32 v[96:97], v[32:33]
	v_mov_b64_e32 v[124:125], v[60:61]
	v_mov_b64_e32 v[118:119], v[54:55]
	v_mov_b64_e32 v[116:117], v[52:53]
	v_mov_b64_e32 v[114:115], v[50:51]
	v_mov_b64_e32 v[112:113], v[48:49]
	v_mov_b64_e32 v[110:111], v[46:47]
	v_mov_b64_e32 v[108:109], v[44:45]
	v_mov_b64_e32 v[106:107], v[42:43]
	v_mov_b64_e32 v[104:105], v[40:41]
	v_mov_b64_e32 v[102:103], v[38:39]
	v_mov_b64_e32 v[100:101], v[36:37]
	v_mov_b64_e32 v[98:99], v[34:35]
	v_mov_b32_e32 v120, s7
	v_mov_b32_e32 v121, s7
	v_mov_b32_e32 v122, s7
	v_mov_b32_e32 v123, s7
	v_mov_b64_e32 v[0:1], v[96:97]
	v_mov_b64_e32 v[28:29], v[124:125]
	v_mov_b64_e32 v[30:31], v[126:127]
	v_mov_b64_e32 v[2:3], v[98:99]
	v_mov_b64_e32 v[4:5], v[100:101]
	v_mov_b64_e32 v[6:7], v[102:103]
	v_mov_b64_e32 v[8:9], v[104:105]
	v_mov_b64_e32 v[10:11], v[106:107]
	v_mov_b64_e32 v[12:13], v[108:109]
	v_mov_b64_e32 v[14:15], v[110:111]
	v_mov_b64_e32 v[16:17], v[112:113]
	v_mov_b64_e32 v[18:19], v[114:115]
	v_mov_b64_e32 v[20:21], v[116:117]
	v_mov_b64_e32 v[22:23], v[118:119]
	v_mov_b64_e32 v[24:25], v[120:121]
	v_mov_b64_e32 v[26:27], v[122:123]
	v_mov_b32_e32 v28, s7
	v_mov_b32_e32 v29, s7
	v_mov_b32_e32 v30, s7
	v_mov_b32_e32 v31, s7
	v_mov_b64_e32 v[174:175], v[142:143]
	v_mov_b64_e32 v[172:173], v[140:141]
	s_or_b64 exec, exec, s[0:1]
	v_cmp_gt_i32_e32 vcc, s29, v204
	s_and_saveexec_b64 s[0:1], vcc
	s_cbranch_execz .LBB0_497
.LBB0_533:
	v_lshlrev_b64 v[0:1], 13, v[204:205]
	v_lshl_add_u64 v[0:1], v[206:207], 0, v[0:1]
	v_add_co_u32_e32 v0, vcc, 0x40000, v0
	s_nop 1
	v_addc_co_u32_e32 v1, vcc, 0, v1, vcc
	global_load_dwordx4 v[176:179], v[0:1], off nt
	s_waitcnt vmcnt(0)
	v_mov_b64_e32 v[32:33], v[160:161]
	v_mov_b64_e32 v[52:53], v[180:181]
	v_mov_b64_e32 v[54:55], v[182:183]
	v_mov_b64_e32 v[62:63], v[190:191]
	v_mov_b64_e32 v[34:35], v[162:163]
	v_mov_b64_e32 v[36:37], v[164:165]
	v_mov_b64_e32 v[38:39], v[166:167]
	v_mov_b64_e32 v[40:41], v[168:169]
	v_mov_b64_e32 v[42:43], v[170:171]
	v_mov_b64_e32 v[44:45], v[172:173]
	v_mov_b64_e32 v[46:47], v[174:175]
	v_mov_b64_e32 v[56:57], v[184:185]
	v_mov_b64_e32 v[58:59], v[186:187]
	v_mov_b64_e32 v[60:61], v[188:189]
	v_mov_b32_e32 v52, s7
	v_mov_b32_e32 v53, s7
	v_mov_b32_e32 v54, s7
	v_mov_b32_e32 v55, s7
	v_mov_b64_e32 v[64:65], v[160:161]
	v_mov_b64_e32 v[66:67], v[162:163]
	v_mov_b64_e32 v[68:69], v[164:165]
	v_mov_b64_e32 v[70:71], v[166:167]
	v_mov_b64_e32 v[72:73], v[168:169]
	v_mov_b64_e32 v[74:75], v[170:171]
	v_mov_b64_e32 v[76:77], v[172:173]
	v_mov_b64_e32 v[78:79], v[174:175]
	v_mov_b64_e32 v[88:89], v[184:185]
	v_mov_b64_e32 v[90:91], v[186:187]
	v_mov_b64_e32 v[92:93], v[188:189]
	v_mov_b64_e32 v[94:95], v[190:191]
	v_mov_b64_e32 v[84:85], v[180:181]
	v_mov_b64_e32 v[86:87], v[182:183]
	v_mov_b64_e32 v[48:49], v[176:177]
	v_mov_b64_e32 v[50:51], v[178:179]
	v_mov_b64_e32 v[126:127], v[62:63]
	v_mov_b64_e32 v[122:123], v[58:59]
	v_mov_b64_e32 v[120:121], v[56:57]
	v_mov_b64_e32 v[96:97], v[32:33]
	v_mov_b64_e32 v[124:125], v[60:61]
	v_mov_b64_e32 v[118:119], v[54:55]
	v_mov_b64_e32 v[116:117], v[52:53]
	v_mov_b64_e32 v[114:115], v[50:51]
	v_mov_b64_e32 v[112:113], v[48:49]
	v_mov_b64_e32 v[110:111], v[46:47]
	v_mov_b64_e32 v[108:109], v[44:45]
	v_mov_b64_e32 v[106:107], v[42:43]
	v_mov_b64_e32 v[104:105], v[40:41]
	v_mov_b64_e32 v[102:103], v[38:39]
	v_mov_b64_e32 v[100:101], v[36:37]
	v_mov_b64_e32 v[98:99], v[34:35]
	v_mov_b32_e32 v120, s7
	v_mov_b32_e32 v121, s7
	v_mov_b32_e32 v122, s7
	v_mov_b32_e32 v123, s7
	v_mov_b64_e32 v[0:1], v[96:97]
	v_mov_b64_e32 v[28:29], v[124:125]
	v_mov_b64_e32 v[30:31], v[126:127]
	v_mov_b64_e32 v[2:3], v[98:99]
	v_mov_b64_e32 v[4:5], v[100:101]
	v_mov_b64_e32 v[6:7], v[102:103]
	v_mov_b64_e32 v[8:9], v[104:105]
	v_mov_b64_e32 v[10:11], v[106:107]
	v_mov_b64_e32 v[12:13], v[108:109]
	v_mov_b64_e32 v[14:15], v[110:111]
	v_mov_b64_e32 v[16:17], v[112:113]
	v_mov_b64_e32 v[18:19], v[114:115]
	v_mov_b64_e32 v[20:21], v[116:117]
	v_mov_b64_e32 v[22:23], v[118:119]
	v_mov_b64_e32 v[24:25], v[120:121]
	v_mov_b64_e32 v[26:27], v[122:123]
	v_mov_b32_e32 v28, s7
	v_mov_b32_e32 v29, s7
	v_mov_b32_e32 v30, s7
	v_mov_b32_e32 v31, s7
	v_mov_b64_e32 v[80:81], v[176:177]
	v_mov_b64_e32 v[82:83], v[178:179]
	s_or_b64 exec, exec, s[0:1]
	v_cmp_gt_i32_e32 vcc, s30, v204
	s_and_saveexec_b64 s[0:1], vcc
	s_cbranch_execz .LBB0_498
.LBB0_534:
	v_lshlrev_b64 v[0:1], 13, v[204:205]
	v_lshl_add_u64 v[0:1], v[206:207], 0, v[0:1]
	v_add_co_u32_e32 v0, vcc, 0x50000, v0
	s_nop 1
	v_addc_co_u32_e32 v1, vcc, 0, v1, vcc
	global_load_dwordx4 v[84:87], v[0:1], off nt
	s_waitcnt vmcnt(0)
	v_mov_b64_e32 v[126:127], v[94:95]
	v_mov_b64_e32 v[122:123], v[90:91]
	v_mov_b64_e32 v[120:121], v[88:89]
	v_mov_b64_e32 v[96:97], v[64:65]
	v_mov_b64_e32 v[124:125], v[92:93]
	v_mov_b64_e32 v[114:115], v[82:83]
	v_mov_b64_e32 v[112:113], v[80:81]
	v_mov_b64_e32 v[110:111], v[78:79]
	v_mov_b64_e32 v[108:109], v[76:77]
	v_mov_b64_e32 v[106:107], v[74:75]
	v_mov_b64_e32 v[104:105], v[72:73]
	v_mov_b64_e32 v[102:103], v[70:71]
	v_mov_b64_e32 v[100:101], v[68:69]
	v_mov_b64_e32 v[98:99], v[66:67]
	v_mov_b32_e32 v120, s7
	v_mov_b32_e32 v121, s7
	v_mov_b32_e32 v122, s7
	v_mov_b32_e32 v123, s7
	v_mov_b64_e32 v[32:33], v[64:65]
	v_mov_b64_e32 v[34:35], v[66:67]
	v_mov_b64_e32 v[36:37], v[68:69]
	v_mov_b64_e32 v[38:39], v[70:71]
	v_mov_b64_e32 v[40:41], v[72:73]
	v_mov_b64_e32 v[42:43], v[74:75]
	v_mov_b64_e32 v[44:45], v[76:77]
	v_mov_b64_e32 v[46:47], v[78:79]
	v_mov_b64_e32 v[48:49], v[80:81]
	v_mov_b64_e32 v[50:51], v[82:83]
	v_mov_b64_e32 v[60:61], v[92:93]
	v_mov_b64_e32 v[62:63], v[94:95]
	v_mov_b64_e32 v[56:57], v[88:89]
	v_mov_b64_e32 v[58:59], v[90:91]
	v_mov_b64_e32 v[118:119], v[86:87]
	v_mov_b64_e32 v[116:117], v[84:85]
	v_mov_b64_e32 v[0:1], v[96:97]
	v_mov_b64_e32 v[28:29], v[124:125]
	v_mov_b64_e32 v[30:31], v[126:127]
	v_mov_b64_e32 v[2:3], v[98:99]
	v_mov_b64_e32 v[4:5], v[100:101]
	v_mov_b64_e32 v[6:7], v[102:103]
	v_mov_b64_e32 v[8:9], v[104:105]
	v_mov_b64_e32 v[10:11], v[106:107]
	v_mov_b64_e32 v[12:13], v[108:109]
	v_mov_b64_e32 v[14:15], v[110:111]
	v_mov_b64_e32 v[16:17], v[112:113]
	v_mov_b64_e32 v[18:19], v[114:115]
	v_mov_b64_e32 v[20:21], v[116:117]
	v_mov_b64_e32 v[22:23], v[118:119]
	v_mov_b64_e32 v[24:25], v[120:121]
	v_mov_b64_e32 v[26:27], v[122:123]
	v_mov_b32_e32 v28, s7
	v_mov_b32_e32 v29, s7
	v_mov_b32_e32 v30, s7
	v_mov_b32_e32 v31, s7
	v_mov_b64_e32 v[52:53], v[84:85]
	v_mov_b64_e32 v[54:55], v[86:87]
	s_or_b64 exec, exec, s[0:1]
	v_cmp_gt_i32_e32 vcc, s31, v204
	s_and_saveexec_b64 s[0:1], vcc
	s_cbranch_execz .LBB0_499
.LBB0_535:
	v_lshlrev_b64 v[0:1], 13, v[204:205]
	v_lshl_add_u64 v[0:1], v[206:207], 0, v[0:1]
	v_add_co_u32_e32 v0, vcc, 0x60000, v0
	s_nop 1
	v_addc_co_u32_e32 v1, vcc, 0, v1, vcc
	global_load_dwordx4 v[56:59], v[0:1], off nt
	s_waitcnt vmcnt(0)
	v_mov_b64_e32 v[0:1], v[32:33]
	v_mov_b64_e32 v[28:29], v[60:61]
	v_mov_b64_e32 v[30:31], v[62:63]
	v_mov_b64_e32 v[126:127], v[62:63]
	v_mov_b64_e32 v[2:3], v[34:35]
	v_mov_b64_e32 v[4:5], v[36:37]
	v_mov_b64_e32 v[6:7], v[38:39]
	v_mov_b64_e32 v[8:9], v[40:41]
	v_mov_b64_e32 v[10:11], v[42:43]
	v_mov_b64_e32 v[12:13], v[44:45]
	v_mov_b64_e32 v[14:15], v[46:47]
	v_mov_b64_e32 v[16:17], v[48:49]
	v_mov_b64_e32 v[18:19], v[50:51]
	v_mov_b64_e32 v[20:21], v[52:53]
	v_mov_b64_e32 v[22:23], v[54:55]
	v_mov_b32_e32 v28, s7
	v_mov_b32_e32 v29, s7
	v_mov_b32_e32 v30, s7
	v_mov_b32_e32 v31, s7
	v_mov_b64_e32 v[118:119], v[54:55]
	v_mov_b64_e32 v[116:117], v[52:53]
	v_mov_b64_e32 v[114:115], v[50:51]
	v_mov_b64_e32 v[112:113], v[48:49]
	v_mov_b64_e32 v[110:111], v[46:47]
	v_mov_b64_e32 v[108:109], v[44:45]
	v_mov_b64_e32 v[106:107], v[42:43]
	v_mov_b64_e32 v[104:105], v[40:41]
	v_mov_b64_e32 v[102:103], v[38:39]
	v_mov_b64_e32 v[100:101], v[36:37]
	v_mov_b64_e32 v[98:99], v[34:35]
	v_mov_b64_e32 v[96:97], v[32:33]
	v_mov_b64_e32 v[124:125], v[60:61]
	v_mov_b64_e32 v[24:25], v[56:57]
	v_mov_b64_e32 v[26:27], v[58:59]
	v_mov_b64_e32 v[122:123], v[58:59]
	v_mov_b64_e32 v[120:121], v[56:57]
	s_or_b64 exec, exec, s[0:1]
	v_cmp_gt_i32_e32 vcc, s33, v204
	s_and_saveexec_b64 s[0:1], vcc
	s_cbranch_execnz .LBB0_500
	s_branch .LBB0_501

.LBB0_537:
	v_lshlrev_b64 v[4:5], 13, v[204:205]
	v_lshl_add_u64 v[4:5], v[206:207], 0, v[4:5]
	v_add_co_u32_e32 v4, vcc, 0x10000, v4
	s_nop 1
	v_addc_co_u32_e32 v5, vcc, 0, v5, vcc
	global_load_dwordx4 v[4:7], v[4:5], off nt
	s_waitcnt vmcnt(0)
	v_mov_b64_e32 v[158:159], v[30:31]
	v_mov_b64_e32 v[138:139], v[10:11]
	v_mov_b64_e32 v[136:137], v[8:9]
	v_mov_b64_e32 v[156:157], v[28:29]
	v_mov_b64_e32 v[154:155], v[26:27]
	v_mov_b64_e32 v[152:153], v[24:25]
	v_mov_b64_e32 v[150:151], v[22:23]
	v_mov_b64_e32 v[148:149], v[20:21]
	v_mov_b64_e32 v[146:147], v[18:19]
	v_mov_b64_e32 v[144:145], v[16:17]
	v_mov_b64_e32 v[142:143], v[14:15]
	v_mov_b64_e32 v[140:141], v[12:13]
	v_mov_b64_e32 v[130:131], v[2:3]
	v_mov_b64_e32 v[128:129], v[0:1]
	v_mov_b32_e32 v136, s7
	v_mov_b32_e32 v137, s7
	v_mov_b32_e32 v138, s7
	v_mov_b32_e32 v139, s7
	v_mov_b64_e32 v[134:135], v[6:7]
	v_mov_b64_e32 v[132:133], v[4:5]
	v_mov_b64_e32 v[190:191], v[158:159]
	v_mov_b64_e32 v[174:175], v[142:143]
	v_mov_b64_e32 v[172:173], v[140:141]
	v_mov_b64_e32 v[160:161], v[128:129]
	v_mov_b64_e32 v[188:189], v[156:157]
	v_mov_b64_e32 v[186:187], v[154:155]
	v_mov_b64_e32 v[184:185], v[152:153]
	v_mov_b64_e32 v[182:183], v[150:151]
	v_mov_b64_e32 v[180:181], v[148:149]
	v_mov_b64_e32 v[178:179], v[146:147]
	v_mov_b64_e32 v[176:177], v[144:145]
	v_mov_b64_e32 v[170:171], v[138:139]
	v_mov_b64_e32 v[168:169], v[136:137]
	v_mov_b64_e32 v[166:167], v[134:135]
	v_mov_b64_e32 v[164:165], v[132:133]
	v_mov_b64_e32 v[162:163], v[130:131]
	v_mov_b32_e32 v172, s7
	v_mov_b32_e32 v173, s7
	v_mov_b32_e32 v174, s7
	v_mov_b32_e32 v175, s7
	v_mov_b64_e32 v[64:65], v[160:161]
	v_mov_b64_e32 v[80:81], v[176:177]
	v_mov_b64_e32 v[82:83], v[178:179]
	v_mov_b64_e32 v[66:67], v[162:163]
	v_mov_b64_e32 v[68:69], v[164:165]
	v_mov_b64_e32 v[70:71], v[166:167]
	v_mov_b64_e32 v[72:73], v[168:169]
	v_mov_b64_e32 v[74:75], v[170:171]
	v_mov_b64_e32 v[76:77], v[172:173]
	v_mov_b64_e32 v[78:79], v[174:175]
	v_mov_b64_e32 v[84:85], v[180:181]
	v_mov_b64_e32 v[86:87], v[182:183]
	v_mov_b64_e32 v[88:89], v[184:185]
	v_mov_b64_e32 v[90:91], v[186:187]
	v_mov_b64_e32 v[92:93], v[188:189]
	v_mov_b64_e32 v[94:95], v[190:191]
	v_mov_b32_e32 v80, s7
	v_mov_b32_e32 v81, s7
	v_mov_b32_e32 v82, s7
	v_mov_b32_e32 v83, s7
	v_mov_b64_e32 v[32:33], v[64:65]
	v_mov_b64_e32 v[52:53], v[84:85]
	v_mov_b64_e32 v[54:55], v[86:87]
	v_mov_b64_e32 v[62:63], v[94:95]
	v_mov_b64_e32 v[34:35], v[66:67]
	v_mov_b64_e32 v[36:37], v[68:69]
	v_mov_b64_e32 v[38:39], v[70:71]
	v_mov_b64_e32 v[40:41], v[72:73]
	v_mov_b64_e32 v[42:43], v[74:75]
	v_mov_b64_e32 v[44:45], v[76:77]
	v_mov_b64_e32 v[46:47], v[78:79]
	v_mov_b64_e32 v[48:49], v[80:81]
	v_mov_b64_e32 v[50:51], v[82:83]
	v_mov_b64_e32 v[56:57], v[88:89]
	v_mov_b64_e32 v[58:59], v[90:91]
	v_mov_b64_e32 v[60:61], v[92:93]
	v_mov_b32_e32 v52, s7
	v_mov_b32_e32 v53, s7
	v_mov_b32_e32 v54, s7
	v_mov_b32_e32 v55, s7
	v_mov_b64_e32 v[126:127], v[62:63]
	v_mov_b64_e32 v[122:123], v[58:59]
	v_mov_b64_e32 v[120:121], v[56:57]
	v_mov_b64_e32 v[96:97], v[32:33]
	v_mov_b64_e32 v[124:125], v[60:61]
	v_mov_b64_e32 v[118:119], v[54:55]
	v_mov_b64_e32 v[116:117], v[52:53]
	v_mov_b64_e32 v[114:115], v[50:51]
	v_mov_b64_e32 v[112:113], v[48:49]
	v_mov_b64_e32 v[110:111], v[46:47]
	v_mov_b64_e32 v[108:109], v[44:45]
	v_mov_b64_e32 v[106:107], v[42:43]
	v_mov_b64_e32 v[104:105], v[40:41]
	v_mov_b64_e32 v[102:103], v[38:39]
	v_mov_b64_e32 v[100:101], v[36:37]
	v_mov_b64_e32 v[98:99], v[34:35]
	v_mov_b32_e32 v120, s7
	v_mov_b32_e32 v121, s7
	v_mov_b32_e32 v122, s7
	v_mov_b32_e32 v123, s7
	v_mov_b64_e32 v[0:1], v[96:97]
	v_mov_b64_e32 v[28:29], v[124:125]
	v_mov_b64_e32 v[30:31], v[126:127]
	v_mov_b64_e32 v[2:3], v[98:99]
	v_mov_b64_e32 v[4:5], v[100:101]
	v_mov_b64_e32 v[6:7], v[102:103]
	v_mov_b64_e32 v[8:9], v[104:105]
	v_mov_b64_e32 v[10:11], v[106:107]
	v_mov_b64_e32 v[12:13], v[108:109]
	v_mov_b64_e32 v[14:15], v[110:111]
	v_mov_b64_e32 v[16:17], v[112:113]
	v_mov_b64_e32 v[18:19], v[114:115]
	v_mov_b64_e32 v[20:21], v[116:117]
	v_mov_b64_e32 v[22:23], v[118:119]
	v_mov_b64_e32 v[24:25], v[120:121]
	v_mov_b64_e32 v[26:27], v[122:123]
	v_mov_b32_e32 v28, s7
	v_mov_b32_e32 v29, s7
	v_mov_b32_e32 v30, s7
	v_mov_b32_e32 v31, s7
	s_or_b64 exec, exec, s[0:1]
	v_cmp_gt_i32_e32 vcc, s23, v204
	s_and_saveexec_b64 s[0:1], vcc
	s_cbranch_execz .LBB0_480
.LBB0_538:
	v_lshlrev_b64 v[0:1], 13, v[204:205]
	v_lshl_add_u64 v[0:1], v[206:207], 0, v[0:1]
	v_add_co_u32_e32 v0, vcc, 0x20000, v0
	s_nop 1
	v_addc_co_u32_e32 v1, vcc, 0, v1, vcc
	global_load_dwordx4 v[136:139], v[0:1], off nt
	s_waitcnt vmcnt(0)
	v_mov_b64_e32 v[190:191], v[158:159]
	v_mov_b64_e32 v[174:175], v[142:143]
	v_mov_b64_e32 v[172:173], v[140:141]
	v_mov_b64_e32 v[160:161], v[128:129]
	v_mov_b64_e32 v[188:189], v[156:157]
	v_mov_b64_e32 v[186:187], v[154:155]
	v_mov_b64_e32 v[184:185], v[152:153]
	v_mov_b64_e32 v[182:183], v[150:151]
	v_mov_b64_e32 v[180:181], v[148:149]
	v_mov_b64_e32 v[178:179], v[146:147]
	v_mov_b64_e32 v[176:177], v[144:145]
	v_mov_b64_e32 v[166:167], v[134:135]
	v_mov_b64_e32 v[164:165], v[132:133]
	v_mov_b64_e32 v[162:163], v[130:131]
	v_mov_b32_e32 v172, s7
	v_mov_b32_e32 v173, s7
	v_mov_b32_e32 v174, s7
	v_mov_b32_e32 v175, s7
	v_mov_b64_e32 v[170:171], v[138:139]
	v_mov_b64_e32 v[168:169], v[136:137]
	v_mov_b64_e32 v[64:65], v[160:161]
	v_mov_b64_e32 v[80:81], v[176:177]
	v_mov_b64_e32 v[82:83], v[178:179]
	v_mov_b64_e32 v[66:67], v[162:163]
	v_mov_b64_e32 v[68:69], v[164:165]
	v_mov_b64_e32 v[70:71], v[166:167]
	v_mov_b64_e32 v[72:73], v[168:169]
	v_mov_b64_e32 v[74:75], v[170:171]
	v_mov_b64_e32 v[76:77], v[172:173]
	v_mov_b64_e32 v[78:79], v[174:175]
	v_mov_b64_e32 v[84:85], v[180:181]
	v_mov_b64_e32 v[86:87], v[182:183]
	v_mov_b64_e32 v[88:89], v[184:185]
	v_mov_b64_e32 v[90:91], v[186:187]
	v_mov_b64_e32 v[92:93], v[188:189]
	v_mov_b64_e32 v[94:95], v[190:191]
	v_mov_b32_e32 v80, s7
	v_mov_b32_e32 v81, s7
	v_mov_b32_e32 v82, s7
	v_mov_b32_e32 v83, s7
	v_mov_b64_e32 v[32:33], v[64:65]
	v_mov_b64_e32 v[52:53], v[84:85]
	v_mov_b64_e32 v[54:55], v[86:87]
	v_mov_b64_e32 v[62:63], v[94:95]
	v_mov_b64_e32 v[34:35], v[66:67]
	v_mov_b64_e32 v[36:37], v[68:69]
	v_mov_b64_e32 v[38:39], v[70:71]
	v_mov_b64_e32 v[40:41], v[72:73]
	v_mov_b64_e32 v[42:43], v[74:75]
	v_mov_b64_e32 v[44:45], v[76:77]
	v_mov_b64_e32 v[46:47], v[78:79]
	v_mov_b64_e32 v[48:49], v[80:81]
	v_mov_b64_e32 v[50:51], v[82:83]
	v_mov_b64_e32 v[56:57], v[88:89]
	v_mov_b64_e32 v[58:59], v[90:91]
	v_mov_b64_e32 v[60:61], v[92:93]
	v_mov_b32_e32 v52, s7
	v_mov_b32_e32 v53, s7
	v_mov_b32_e32 v54, s7
	v_mov_b32_e32 v55, s7
	v_mov_b64_e32 v[126:127], v[62:63]
	v_mov_b64_e32 v[122:123], v[58:59]
	v_mov_b64_e32 v[120:121], v[56:57]
	v_mov_b64_e32 v[96:97], v[32:33]
	v_mov_b64_e32 v[124:125], v[60:61]
	v_mov_b64_e32 v[118:119], v[54:55]
	v_mov_b64_e32 v[116:117], v[52:53]
	v_mov_b64_e32 v[114:115], v[50:51]
	v_mov_b64_e32 v[112:113], v[48:49]
	v_mov_b64_e32 v[110:111], v[46:47]
	v_mov_b64_e32 v[108:109], v[44:45]
	v_mov_b64_e32 v[106:107], v[42:43]
	v_mov_b64_e32 v[104:105], v[40:41]
	v_mov_b64_e32 v[102:103], v[38:39]
	v_mov_b64_e32 v[100:101], v[36:37]
	v_mov_b64_e32 v[98:99], v[34:35]
	v_mov_b32_e32 v120, s7
	v_mov_b32_e32 v121, s7
	v_mov_b32_e32 v122, s7
	v_mov_b32_e32 v123, s7
	v_mov_b64_e32 v[0:1], v[96:97]
	v_mov_b64_e32 v[28:29], v[124:125]
	v_mov_b64_e32 v[30:31], v[126:127]
	v_mov_b64_e32 v[2:3], v[98:99]
	v_mov_b64_e32 v[4:5], v[100:101]
	v_mov_b64_e32 v[6:7], v[102:103]
	v_mov_b64_e32 v[8:9], v[104:105]
	v_mov_b64_e32 v[10:11], v[106:107]
	v_mov_b64_e32 v[12:13], v[108:109]
	v_mov_b64_e32 v[14:15], v[110:111]
	v_mov_b64_e32 v[16:17], v[112:113]
	v_mov_b64_e32 v[18:19], v[114:115]
	v_mov_b64_e32 v[20:21], v[116:117]
	v_mov_b64_e32 v[22:23], v[118:119]
	v_mov_b64_e32 v[24:25], v[120:121]
	v_mov_b64_e32 v[26:27], v[122:123]
	v_mov_b32_e32 v28, s7
	v_mov_b32_e32 v29, s7
	v_mov_b32_e32 v30, s7
	v_mov_b32_e32 v31, s7
	s_or_b64 exec, exec, s[0:1]
	v_cmp_gt_i32_e32 vcc, s24, v204
	s_and_saveexec_b64 s[0:1], vcc
	s_cbranch_execz .LBB0_481
.LBB0_539:
	v_lshlrev_b64 v[0:1], 13, v[204:205]
	v_lshl_add_u64 v[0:1], v[206:207], 0, v[0:1]
	v_add_co_u32_e32 v0, vcc, 0x30000, v0
	s_nop 1
	v_addc_co_u32_e32 v1, vcc, 0, v1, vcc
	global_load_dwordx4 v[140:143], v[0:1], off nt
	s_waitcnt vmcnt(0)
	v_mov_b64_e32 v[64:65], v[128:129]
	v_mov_b64_e32 v[80:81], v[144:145]
	v_mov_b64_e32 v[82:83], v[146:147]
	v_mov_b64_e32 v[66:67], v[130:131]
	v_mov_b64_e32 v[68:69], v[132:133]
	v_mov_b64_e32 v[70:71], v[134:135]
	v_mov_b64_e32 v[72:73], v[136:137]
	v_mov_b64_e32 v[74:75], v[138:139]
	v_mov_b64_e32 v[84:85], v[148:149]
	v_mov_b64_e32 v[86:87], v[150:151]
	v_mov_b64_e32 v[88:89], v[152:153]
	v_mov_b64_e32 v[90:91], v[154:155]
	v_mov_b64_e32 v[92:93], v[156:157]
	v_mov_b64_e32 v[94:95], v[158:159]
	v_mov_b32_e32 v80, s7
	v_mov_b32_e32 v81, s7
	v_mov_b32_e32 v82, s7
	v_mov_b32_e32 v83, s7
	v_mov_b64_e32 v[190:191], v[158:159]
	v_mov_b64_e32 v[188:189], v[156:157]
	v_mov_b64_e32 v[186:187], v[154:155]
	v_mov_b64_e32 v[184:185], v[152:153]
	v_mov_b64_e32 v[182:183], v[150:151]
	v_mov_b64_e32 v[180:181], v[148:149]
	v_mov_b64_e32 v[170:171], v[138:139]
	v_mov_b64_e32 v[168:169], v[136:137]
	v_mov_b64_e32 v[166:167], v[134:135]
	v_mov_b64_e32 v[164:165], v[132:133]
	v_mov_b64_e32 v[162:163], v[130:131]
	v_mov_b64_e32 v[160:161], v[128:129]
	v_mov_b64_e32 v[178:179], v[146:147]
	v_mov_b64_e32 v[176:177], v[144:145]
	v_mov_b64_e32 v[76:77], v[140:141]
	v_mov_b64_e32 v[78:79], v[142:143]
	v_mov_b64_e32 v[32:33], v[64:65]
	v_mov_b64_e32 v[52:53], v[84:85]
	v_mov_b64_e32 v[54:55], v[86:87]
	v_mov_b64_e32 v[62:63], v[94:95]
	v_mov_b64_e32 v[34:35], v[66:67]
	v_mov_b64_e32 v[36:37], v[68:69]
	v_mov_b64_e32 v[38:39], v[70:71]
	v_mov_b64_e32 v[40:41], v[72:73]
	v_mov_b64_e32 v[42:43], v[74:75]
	v_mov_b64_e32 v[44:45], v[76:77]
	v_mov_b64_e32 v[46:47], v[78:79]
	v_mov_b64_e32 v[48:49], v[80:81]
	v_mov_b64_e32 v[50:51], v[82:83]
	v_mov_b64_e32 v[56:57], v[88:89]
	v_mov_b64_e32 v[58:59], v[90:91]
	v_mov_b64_e32 v[60:61], v[92:93]
	v_mov_b32_e32 v52, s7
	v_mov_b32_e32 v53, s7
	v_mov_b32_e32 v54, s7
	v_mov_b32_e32 v55, s7
	v_mov_b64_e32 v[126:127], v[62:63]
	v_mov_b64_e32 v[122:123], v[58:59]
	v_mov_b64_e32 v[120:121], v[56:57]
	v_mov_b64_e32 v[96:97], v[32:33]
	v_mov_b64_e32 v[124:125], v[60:61]
	v_mov_b64_e32 v[118:119], v[54:55]
	v_mov_b64_e32 v[116:117], v[52:53]
	v_mov_b64_e32 v[114:115], v[50:51]
	v_mov_b64_e32 v[112:113], v[48:49]
	v_mov_b64_e32 v[110:111], v[46:47]
	v_mov_b64_e32 v[108:109], v[44:45]
	v_mov_b64_e32 v[106:107], v[42:43]
	v_mov_b64_e32 v[104:105], v[40:41]
	v_mov_b64_e32 v[102:103], v[38:39]
	v_mov_b64_e32 v[100:101], v[36:37]
	v_mov_b64_e32 v[98:99], v[34:35]
	v_mov_b32_e32 v120, s7
	v_mov_b32_e32 v121, s7
	v_mov_b32_e32 v122, s7
	v_mov_b32_e32 v123, s7
	v_mov_b64_e32 v[0:1], v[96:97]
	v_mov_b64_e32 v[28:29], v[124:125]
	v_mov_b64_e32 v[30:31], v[126:127]
	v_mov_b64_e32 v[2:3], v[98:99]
	v_mov_b64_e32 v[4:5], v[100:101]
	v_mov_b64_e32 v[6:7], v[102:103]
	v_mov_b64_e32 v[8:9], v[104:105]
	v_mov_b64_e32 v[10:11], v[106:107]
	v_mov_b64_e32 v[12:13], v[108:109]
	v_mov_b64_e32 v[14:15], v[110:111]
	v_mov_b64_e32 v[16:17], v[112:113]
	v_mov_b64_e32 v[18:19], v[114:115]
	v_mov_b64_e32 v[20:21], v[116:117]
	v_mov_b64_e32 v[22:23], v[118:119]
	v_mov_b64_e32 v[24:25], v[120:121]
	v_mov_b64_e32 v[26:27], v[122:123]
	v_mov_b32_e32 v28, s7
	v_mov_b32_e32 v29, s7
	v_mov_b32_e32 v30, s7
	v_mov_b32_e32 v31, s7
	v_mov_b64_e32 v[174:175], v[142:143]
	v_mov_b64_e32 v[172:173], v[140:141]
	s_or_b64 exec, exec, s[0:1]
	v_cmp_gt_i32_e32 vcc, s18, v204
	s_and_saveexec_b64 s[0:1], vcc
	s_cbranch_execz .LBB0_482
.LBB0_540:
	v_lshlrev_b64 v[0:1], 13, v[204:205]
	v_lshl_add_u64 v[0:1], v[206:207], 0, v[0:1]
	v_add_co_u32_e32 v0, vcc, 0x40000, v0
	s_nop 1
	v_addc_co_u32_e32 v1, vcc, 0, v1, vcc
	global_load_dwordx4 v[176:179], v[0:1], off nt
	s_waitcnt vmcnt(0)
	v_mov_b64_e32 v[32:33], v[160:161]
	v_mov_b64_e32 v[52:53], v[180:181]
	v_mov_b64_e32 v[54:55], v[182:183]
	v_mov_b64_e32 v[62:63], v[190:191]
	v_mov_b64_e32 v[34:35], v[162:163]
	v_mov_b64_e32 v[36:37], v[164:165]
	v_mov_b64_e32 v[38:39], v[166:167]
	v_mov_b64_e32 v[40:41], v[168:169]
	v_mov_b64_e32 v[42:43], v[170:171]
	v_mov_b64_e32 v[44:45], v[172:173]
	v_mov_b64_e32 v[46:47], v[174:175]
	v_mov_b64_e32 v[56:57], v[184:185]
	v_mov_b64_e32 v[58:59], v[186:187]
	v_mov_b64_e32 v[60:61], v[188:189]
	v_mov_b32_e32 v52, s7
	v_mov_b32_e32 v53, s7
	v_mov_b32_e32 v54, s7
	v_mov_b32_e32 v55, s7
	v_mov_b64_e32 v[64:65], v[160:161]
	v_mov_b64_e32 v[66:67], v[162:163]
	v_mov_b64_e32 v[68:69], v[164:165]
	v_mov_b64_e32 v[70:71], v[166:167]
	v_mov_b64_e32 v[72:73], v[168:169]
	v_mov_b64_e32 v[74:75], v[170:171]
	v_mov_b64_e32 v[76:77], v[172:173]
	v_mov_b64_e32 v[78:79], v[174:175]
	v_mov_b64_e32 v[88:89], v[184:185]
	v_mov_b64_e32 v[90:91], v[186:187]
	v_mov_b64_e32 v[92:93], v[188:189]
	v_mov_b64_e32 v[94:95], v[190:191]
	v_mov_b64_e32 v[84:85], v[180:181]
	v_mov_b64_e32 v[86:87], v[182:183]
	v_mov_b64_e32 v[48:49], v[176:177]
	v_mov_b64_e32 v[50:51], v[178:179]
	v_mov_b64_e32 v[126:127], v[62:63]
	v_mov_b64_e32 v[122:123], v[58:59]
	v_mov_b64_e32 v[120:121], v[56:57]
	v_mov_b64_e32 v[96:97], v[32:33]
	v_mov_b64_e32 v[124:125], v[60:61]
	v_mov_b64_e32 v[118:119], v[54:55]
	v_mov_b64_e32 v[116:117], v[52:53]
	v_mov_b64_e32 v[114:115], v[50:51]
	v_mov_b64_e32 v[112:113], v[48:49]
	v_mov_b64_e32 v[110:111], v[46:47]
	v_mov_b64_e32 v[108:109], v[44:45]
	v_mov_b64_e32 v[106:107], v[42:43]
	v_mov_b64_e32 v[104:105], v[40:41]
	v_mov_b64_e32 v[102:103], v[38:39]
	v_mov_b64_e32 v[100:101], v[36:37]
	v_mov_b64_e32 v[98:99], v[34:35]
	v_mov_b32_e32 v120, s7
	v_mov_b32_e32 v121, s7
	v_mov_b32_e32 v122, s7
	v_mov_b32_e32 v123, s7
	v_mov_b64_e32 v[0:1], v[96:97]
	v_mov_b64_e32 v[28:29], v[124:125]
	v_mov_b64_e32 v[30:31], v[126:127]
	v_mov_b64_e32 v[2:3], v[98:99]
	v_mov_b64_e32 v[4:5], v[100:101]
	v_mov_b64_e32 v[6:7], v[102:103]
	v_mov_b64_e32 v[8:9], v[104:105]
	v_mov_b64_e32 v[10:11], v[106:107]
	v_mov_b64_e32 v[12:13], v[108:109]
	v_mov_b64_e32 v[14:15], v[110:111]
	v_mov_b64_e32 v[16:17], v[112:113]
	v_mov_b64_e32 v[18:19], v[114:115]
	v_mov_b64_e32 v[20:21], v[116:117]
	v_mov_b64_e32 v[22:23], v[118:119]
	v_mov_b64_e32 v[24:25], v[120:121]
	v_mov_b64_e32 v[26:27], v[122:123]
	v_mov_b32_e32 v28, s7
	v_mov_b32_e32 v29, s7
	v_mov_b32_e32 v30, s7
	v_mov_b32_e32 v31, s7
	v_mov_b64_e32 v[80:81], v[176:177]
	v_mov_b64_e32 v[82:83], v[178:179]
	s_or_b64 exec, exec, s[0:1]
	v_cmp_gt_i32_e32 vcc, s25, v204
	s_and_saveexec_b64 s[0:1], vcc
	s_cbranch_execz .LBB0_483
.LBB0_541:
	v_lshlrev_b64 v[0:1], 13, v[204:205]
	v_lshl_add_u64 v[0:1], v[206:207], 0, v[0:1]
	v_add_co_u32_e32 v0, vcc, 0x50000, v0
	s_nop 1
	v_addc_co_u32_e32 v1, vcc, 0, v1, vcc
	global_load_dwordx4 v[84:87], v[0:1], off nt
	s_waitcnt vmcnt(0)
	v_mov_b64_e32 v[126:127], v[94:95]
	v_mov_b64_e32 v[122:123], v[90:91]
	v_mov_b64_e32 v[120:121], v[88:89]
	v_mov_b64_e32 v[96:97], v[64:65]
	v_mov_b64_e32 v[124:125], v[92:93]
	v_mov_b64_e32 v[114:115], v[82:83]
	v_mov_b64_e32 v[112:113], v[80:81]
	v_mov_b64_e32 v[110:111], v[78:79]
	v_mov_b64_e32 v[108:109], v[76:77]
	v_mov_b64_e32 v[106:107], v[74:75]
	v_mov_b64_e32 v[104:105], v[72:73]
	v_mov_b64_e32 v[102:103], v[70:71]
	v_mov_b64_e32 v[100:101], v[68:69]
	v_mov_b64_e32 v[98:99], v[66:67]
	v_mov_b32_e32 v120, s7
	v_mov_b32_e32 v121, s7
	v_mov_b32_e32 v122, s7
	v_mov_b32_e32 v123, s7
	v_mov_b64_e32 v[32:33], v[64:65]
	v_mov_b64_e32 v[34:35], v[66:67]
	v_mov_b64_e32 v[36:37], v[68:69]
	v_mov_b64_e32 v[38:39], v[70:71]
	v_mov_b64_e32 v[40:41], v[72:73]
	v_mov_b64_e32 v[42:43], v[74:75]
	v_mov_b64_e32 v[44:45], v[76:77]
	v_mov_b64_e32 v[46:47], v[78:79]
	v_mov_b64_e32 v[48:49], v[80:81]
	v_mov_b64_e32 v[50:51], v[82:83]
	v_mov_b64_e32 v[60:61], v[92:93]
	v_mov_b64_e32 v[62:63], v[94:95]
	v_mov_b64_e32 v[56:57], v[88:89]
	v_mov_b64_e32 v[58:59], v[90:91]
	v_mov_b64_e32 v[118:119], v[86:87]
	v_mov_b64_e32 v[116:117], v[84:85]
	v_mov_b64_e32 v[0:1], v[96:97]
	v_mov_b64_e32 v[28:29], v[124:125]
	v_mov_b64_e32 v[30:31], v[126:127]
	v_mov_b64_e32 v[2:3], v[98:99]
	v_mov_b64_e32 v[4:5], v[100:101]
	v_mov_b64_e32 v[6:7], v[102:103]
	v_mov_b64_e32 v[8:9], v[104:105]
	v_mov_b64_e32 v[10:11], v[106:107]
	v_mov_b64_e32 v[12:13], v[108:109]
	v_mov_b64_e32 v[14:15], v[110:111]
	v_mov_b64_e32 v[16:17], v[112:113]
	v_mov_b64_e32 v[18:19], v[114:115]
	v_mov_b64_e32 v[20:21], v[116:117]
	v_mov_b64_e32 v[22:23], v[118:119]
	v_mov_b64_e32 v[24:25], v[120:121]
	v_mov_b64_e32 v[26:27], v[122:123]
	v_mov_b32_e32 v28, s7
	v_mov_b32_e32 v29, s7
	v_mov_b32_e32 v30, s7
	v_mov_b32_e32 v31, s7
	v_mov_b64_e32 v[52:53], v[84:85]
	v_mov_b64_e32 v[54:55], v[86:87]
	s_or_b64 exec, exec, s[0:1]
	v_cmp_gt_i32_e32 vcc, s26, v204
	s_and_saveexec_b64 s[0:1], vcc
	s_cbranch_execz .LBB0_484
.LBB0_542:
	v_lshlrev_b64 v[0:1], 13, v[204:205]
	v_lshl_add_u64 v[0:1], v[206:207], 0, v[0:1]
	v_add_co_u32_e32 v0, vcc, 0x60000, v0
	s_nop 1
	v_addc_co_u32_e32 v1, vcc, 0, v1, vcc
	global_load_dwordx4 v[56:59], v[0:1], off nt
	s_waitcnt vmcnt(0)
	v_mov_b64_e32 v[0:1], v[32:33]
	v_mov_b64_e32 v[28:29], v[60:61]
	v_mov_b64_e32 v[30:31], v[62:63]
	v_mov_b64_e32 v[126:127], v[62:63]
	v_mov_b64_e32 v[2:3], v[34:35]
	v_mov_b64_e32 v[4:5], v[36:37]
	v_mov_b64_e32 v[6:7], v[38:39]
	v_mov_b64_e32 v[8:9], v[40:41]
	v_mov_b64_e32 v[10:11], v[42:43]
	v_mov_b64_e32 v[12:13], v[44:45]
	v_mov_b64_e32 v[14:15], v[46:47]
	v_mov_b64_e32 v[16:17], v[48:49]
	v_mov_b64_e32 v[18:19], v[50:51]
	v_mov_b64_e32 v[20:21], v[52:53]
	v_mov_b64_e32 v[22:23], v[54:55]
	v_mov_b32_e32 v28, s7
	v_mov_b32_e32 v29, s7
	v_mov_b32_e32 v30, s7
	v_mov_b32_e32 v31, s7
	v_mov_b64_e32 v[118:119], v[54:55]
	v_mov_b64_e32 v[116:117], v[52:53]
	v_mov_b64_e32 v[114:115], v[50:51]
	v_mov_b64_e32 v[112:113], v[48:49]
	v_mov_b64_e32 v[110:111], v[46:47]
	v_mov_b64_e32 v[108:109], v[44:45]
	v_mov_b64_e32 v[106:107], v[42:43]
	v_mov_b64_e32 v[104:105], v[40:41]
	v_mov_b64_e32 v[102:103], v[38:39]
	v_mov_b64_e32 v[100:101], v[36:37]
	v_mov_b64_e32 v[98:99], v[34:35]
	v_mov_b64_e32 v[96:97], v[32:33]
	v_mov_b64_e32 v[124:125], v[60:61]
	v_mov_b64_e32 v[24:25], v[56:57]
	v_mov_b64_e32 v[26:27], v[58:59]
	v_mov_b64_e32 v[122:123], v[58:59]
	v_mov_b64_e32 v[120:121], v[56:57]
	s_or_b64 exec, exec, s[0:1]
	v_cmp_gt_i32_e32 vcc, s27, v204
	s_and_saveexec_b64 s[0:1], vcc
	s_cbranch_execnz .LBB0_485
	s_branch .LBB0_486
.LBB0_543:
	v_add_u32_e32 v4, 8, v206
	v_mad_i64_i32 v[4:5], s[4:5], v4, s21, v[204:205]
	global_load_dwordx4 v[4:7], v[4:5], off nt
	s_waitcnt vmcnt(0)
	v_mov_b64_e32 v[158:159], v[30:31]
	v_mov_b64_e32 v[138:139], v[10:11]
	v_mov_b64_e32 v[136:137], v[8:9]
	v_mov_b64_e32 v[156:157], v[28:29]
	v_mov_b64_e32 v[154:155], v[26:27]
	v_mov_b64_e32 v[152:153], v[24:25]
	v_mov_b64_e32 v[150:151], v[22:23]
	v_mov_b64_e32 v[148:149], v[20:21]
	v_mov_b64_e32 v[146:147], v[18:19]
	v_mov_b64_e32 v[144:145], v[16:17]
	v_mov_b64_e32 v[142:143], v[14:15]
	v_mov_b64_e32 v[140:141], v[12:13]
	v_mov_b64_e32 v[130:131], v[2:3]
	v_mov_b64_e32 v[128:129], v[0:1]
	v_mov_b32_e32 v136, s7
	v_mov_b32_e32 v137, s7
	v_mov_b32_e32 v138, s7
	v_mov_b32_e32 v139, s7
	v_mov_b64_e32 v[134:135], v[6:7]
	v_mov_b64_e32 v[132:133], v[4:5]
	v_mov_b64_e32 v[190:191], v[158:159]
	v_mov_b64_e32 v[174:175], v[142:143]
	v_mov_b64_e32 v[172:173], v[140:141]
	v_mov_b64_e32 v[160:161], v[128:129]
	v_mov_b64_e32 v[188:189], v[156:157]
	v_mov_b64_e32 v[186:187], v[154:155]
	v_mov_b64_e32 v[184:185], v[152:153]
	v_mov_b64_e32 v[182:183], v[150:151]
	v_mov_b64_e32 v[180:181], v[148:149]
	v_mov_b64_e32 v[178:179], v[146:147]
	v_mov_b64_e32 v[176:177], v[144:145]
	v_mov_b64_e32 v[170:171], v[138:139]
	v_mov_b64_e32 v[168:169], v[136:137]
	v_mov_b64_e32 v[166:167], v[134:135]
	v_mov_b64_e32 v[164:165], v[132:133]
	v_mov_b64_e32 v[162:163], v[130:131]
	v_mov_b32_e32 v172, s7
	v_mov_b32_e32 v173, s7
	v_mov_b32_e32 v174, s7
	v_mov_b32_e32 v175, s7
	v_mov_b64_e32 v[64:65], v[160:161]
	v_mov_b64_e32 v[80:81], v[176:177]
	v_mov_b64_e32 v[82:83], v[178:179]
	v_mov_b64_e32 v[66:67], v[162:163]
	v_mov_b64_e32 v[68:69], v[164:165]
	v_mov_b64_e32 v[70:71], v[166:167]
	v_mov_b64_e32 v[72:73], v[168:169]
	v_mov_b64_e32 v[74:75], v[170:171]
	v_mov_b64_e32 v[76:77], v[172:173]
	v_mov_b64_e32 v[78:79], v[174:175]
	v_mov_b64_e32 v[84:85], v[180:181]
	v_mov_b64_e32 v[86:87], v[182:183]
	v_mov_b64_e32 v[88:89], v[184:185]
	v_mov_b64_e32 v[90:91], v[186:187]
	v_mov_b64_e32 v[92:93], v[188:189]
	v_mov_b64_e32 v[94:95], v[190:191]
	v_mov_b32_e32 v80, s7
	v_mov_b32_e32 v81, s7
	v_mov_b32_e32 v82, s7
	v_mov_b32_e32 v83, s7
	v_mov_b64_e32 v[32:33], v[64:65]
	v_mov_b64_e32 v[52:53], v[84:85]
	v_mov_b64_e32 v[54:55], v[86:87]
	v_mov_b64_e32 v[62:63], v[94:95]
	v_mov_b64_e32 v[34:35], v[66:67]
	v_mov_b64_e32 v[36:37], v[68:69]
	v_mov_b64_e32 v[38:39], v[70:71]
	v_mov_b64_e32 v[40:41], v[72:73]
	v_mov_b64_e32 v[42:43], v[74:75]
	v_mov_b64_e32 v[44:45], v[76:77]
	v_mov_b64_e32 v[46:47], v[78:79]
	v_mov_b64_e32 v[48:49], v[80:81]
	v_mov_b64_e32 v[50:51], v[82:83]
	v_mov_b64_e32 v[56:57], v[88:89]
	v_mov_b64_e32 v[58:59], v[90:91]
	v_mov_b64_e32 v[60:61], v[92:93]
	v_mov_b32_e32 v52, s7
	v_mov_b32_e32 v53, s7
	v_mov_b32_e32 v54, s7
	v_mov_b32_e32 v55, s7
	v_mov_b64_e32 v[126:127], v[62:63]
	v_mov_b64_e32 v[122:123], v[58:59]
	v_mov_b64_e32 v[120:121], v[56:57]
	v_mov_b64_e32 v[96:97], v[32:33]
	v_mov_b64_e32 v[124:125], v[60:61]
	v_mov_b64_e32 v[118:119], v[54:55]
	v_mov_b64_e32 v[116:117], v[52:53]
	v_mov_b64_e32 v[114:115], v[50:51]
	v_mov_b64_e32 v[112:113], v[48:49]
	v_mov_b64_e32 v[110:111], v[46:47]
	v_mov_b64_e32 v[108:109], v[44:45]
	v_mov_b64_e32 v[106:107], v[42:43]
	v_mov_b64_e32 v[104:105], v[40:41]
	v_mov_b64_e32 v[102:103], v[38:39]
	v_mov_b64_e32 v[100:101], v[36:37]
	v_mov_b64_e32 v[98:99], v[34:35]
	v_mov_b32_e32 v120, s7
	v_mov_b32_e32 v121, s7
	v_mov_b32_e32 v122, s7
	v_mov_b32_e32 v123, s7
	v_mov_b64_e32 v[0:1], v[96:97]
	v_mov_b64_e32 v[28:29], v[124:125]
	v_mov_b64_e32 v[30:31], v[126:127]
	v_mov_b64_e32 v[2:3], v[98:99]
	v_mov_b64_e32 v[4:5], v[100:101]
	v_mov_b64_e32 v[6:7], v[102:103]
	v_mov_b64_e32 v[8:9], v[104:105]
	v_mov_b64_e32 v[10:11], v[106:107]
	v_mov_b64_e32 v[12:13], v[108:109]
	v_mov_b64_e32 v[14:15], v[110:111]
	v_mov_b64_e32 v[16:17], v[112:113]
	v_mov_b64_e32 v[18:19], v[114:115]
	v_mov_b64_e32 v[20:21], v[116:117]
	v_mov_b64_e32 v[22:23], v[118:119]
	v_mov_b64_e32 v[24:25], v[120:121]
	v_mov_b64_e32 v[26:27], v[122:123]
	v_mov_b32_e32 v28, s7
	v_mov_b32_e32 v29, s7
	v_mov_b32_e32 v30, s7
	v_mov_b32_e32 v31, s7
	s_or_b64 exec, exec, s[0:1]
	v_cmp_gt_i32_e32 vcc, s23, v206
	s_and_saveexec_b64 s[0:1], vcc
	s_cbranch_execz .LBB0_468
.LBB0_544:
	v_add_u32_e32 v0, 16, v206
	v_mad_i64_i32 v[0:1], s[4:5], v0, s21, v[204:205]
	global_load_dwordx4 v[136:139], v[0:1], off nt
	s_waitcnt vmcnt(0)
	v_mov_b64_e32 v[190:191], v[158:159]
	v_mov_b64_e32 v[174:175], v[142:143]
	v_mov_b64_e32 v[172:173], v[140:141]
	v_mov_b64_e32 v[160:161], v[128:129]
	v_mov_b64_e32 v[188:189], v[156:157]
	v_mov_b64_e32 v[186:187], v[154:155]
	v_mov_b64_e32 v[184:185], v[152:153]
	v_mov_b64_e32 v[182:183], v[150:151]
	v_mov_b64_e32 v[180:181], v[148:149]
	v_mov_b64_e32 v[178:179], v[146:147]
	v_mov_b64_e32 v[176:177], v[144:145]
	v_mov_b64_e32 v[166:167], v[134:135]
	v_mov_b64_e32 v[164:165], v[132:133]
	v_mov_b64_e32 v[162:163], v[130:131]
	v_mov_b32_e32 v172, s7
	v_mov_b32_e32 v173, s7
	v_mov_b32_e32 v174, s7
	v_mov_b32_e32 v175, s7
	v_mov_b64_e32 v[170:171], v[138:139]
	v_mov_b64_e32 v[168:169], v[136:137]
	v_mov_b64_e32 v[64:65], v[160:161]
	v_mov_b64_e32 v[80:81], v[176:177]
	v_mov_b64_e32 v[82:83], v[178:179]
	v_mov_b64_e32 v[66:67], v[162:163]
	v_mov_b64_e32 v[68:69], v[164:165]
	v_mov_b64_e32 v[70:71], v[166:167]
	v_mov_b64_e32 v[72:73], v[168:169]
	v_mov_b64_e32 v[74:75], v[170:171]
	v_mov_b64_e32 v[76:77], v[172:173]
	v_mov_b64_e32 v[78:79], v[174:175]
	v_mov_b64_e32 v[84:85], v[180:181]
	v_mov_b64_e32 v[86:87], v[182:183]
	v_mov_b64_e32 v[88:89], v[184:185]
	v_mov_b64_e32 v[90:91], v[186:187]
	v_mov_b64_e32 v[92:93], v[188:189]
	v_mov_b64_e32 v[94:95], v[190:191]
	v_mov_b32_e32 v80, s7
	v_mov_b32_e32 v81, s7
	v_mov_b32_e32 v82, s7
	v_mov_b32_e32 v83, s7
	v_mov_b64_e32 v[32:33], v[64:65]
	v_mov_b64_e32 v[52:53], v[84:85]
	v_mov_b64_e32 v[54:55], v[86:87]
	v_mov_b64_e32 v[62:63], v[94:95]
	v_mov_b64_e32 v[34:35], v[66:67]
	v_mov_b64_e32 v[36:37], v[68:69]
	v_mov_b64_e32 v[38:39], v[70:71]
	v_mov_b64_e32 v[40:41], v[72:73]
	v_mov_b64_e32 v[42:43], v[74:75]
	v_mov_b64_e32 v[44:45], v[76:77]
	v_mov_b64_e32 v[46:47], v[78:79]
	v_mov_b64_e32 v[48:49], v[80:81]
	v_mov_b64_e32 v[50:51], v[82:83]
	v_mov_b64_e32 v[56:57], v[88:89]
	v_mov_b64_e32 v[58:59], v[90:91]
	v_mov_b64_e32 v[60:61], v[92:93]
	v_mov_b32_e32 v52, s7
	v_mov_b32_e32 v53, s7
	v_mov_b32_e32 v54, s7
	v_mov_b32_e32 v55, s7
	v_mov_b64_e32 v[126:127], v[62:63]
	v_mov_b64_e32 v[122:123], v[58:59]
	v_mov_b64_e32 v[120:121], v[56:57]
	v_mov_b64_e32 v[96:97], v[32:33]
	v_mov_b64_e32 v[124:125], v[60:61]
	v_mov_b64_e32 v[118:119], v[54:55]
	v_mov_b64_e32 v[116:117], v[52:53]
	v_mov_b64_e32 v[114:115], v[50:51]
	v_mov_b64_e32 v[112:113], v[48:49]
	v_mov_b64_e32 v[110:111], v[46:47]
	v_mov_b64_e32 v[108:109], v[44:45]
	v_mov_b64_e32 v[106:107], v[42:43]
	v_mov_b64_e32 v[104:105], v[40:41]
	v_mov_b64_e32 v[102:103], v[38:39]
	v_mov_b64_e32 v[100:101], v[36:37]
	v_mov_b64_e32 v[98:99], v[34:35]
	v_mov_b32_e32 v120, s7
	v_mov_b32_e32 v121, s7
	v_mov_b32_e32 v122, s7
	v_mov_b32_e32 v123, s7
	v_mov_b64_e32 v[0:1], v[96:97]
	v_mov_b64_e32 v[28:29], v[124:125]
	v_mov_b64_e32 v[30:31], v[126:127]
	v_mov_b64_e32 v[2:3], v[98:99]
	v_mov_b64_e32 v[4:5], v[100:101]
	v_mov_b64_e32 v[6:7], v[102:103]
	v_mov_b64_e32 v[8:9], v[104:105]
	v_mov_b64_e32 v[10:11], v[106:107]
	v_mov_b64_e32 v[12:13], v[108:109]
	v_mov_b64_e32 v[14:15], v[110:111]
	v_mov_b64_e32 v[16:17], v[112:113]
	v_mov_b64_e32 v[18:19], v[114:115]
	v_mov_b64_e32 v[20:21], v[116:117]
	v_mov_b64_e32 v[22:23], v[118:119]
	v_mov_b64_e32 v[24:25], v[120:121]
	v_mov_b64_e32 v[26:27], v[122:123]
	v_mov_b32_e32 v28, s7
	v_mov_b32_e32 v29, s7
	v_mov_b32_e32 v30, s7
	v_mov_b32_e32 v31, s7
	s_or_b64 exec, exec, s[0:1]
	v_cmp_gt_i32_e32 vcc, s24, v206
	s_and_saveexec_b64 s[0:1], vcc
	s_cbranch_execz .LBB0_469
.LBB0_545:
	v_add_u32_e32 v0, 24, v206
	v_mad_i64_i32 v[0:1], s[4:5], v0, s21, v[204:205]
	global_load_dwordx4 v[140:143], v[0:1], off nt
	s_waitcnt vmcnt(0)
	v_mov_b64_e32 v[64:65], v[128:129]
	v_mov_b64_e32 v[80:81], v[144:145]
	v_mov_b64_e32 v[82:83], v[146:147]
	v_mov_b64_e32 v[66:67], v[130:131]
	v_mov_b64_e32 v[68:69], v[132:133]
	v_mov_b64_e32 v[70:71], v[134:135]
	v_mov_b64_e32 v[72:73], v[136:137]
	v_mov_b64_e32 v[74:75], v[138:139]
	v_mov_b64_e32 v[84:85], v[148:149]
	v_mov_b64_e32 v[86:87], v[150:151]
	v_mov_b64_e32 v[88:89], v[152:153]
	v_mov_b64_e32 v[90:91], v[154:155]
	v_mov_b64_e32 v[92:93], v[156:157]
	v_mov_b64_e32 v[94:95], v[158:159]
	v_mov_b32_e32 v80, s7
	v_mov_b32_e32 v81, s7
	v_mov_b32_e32 v82, s7
	v_mov_b32_e32 v83, s7
	v_mov_b64_e32 v[190:191], v[158:159]
	v_mov_b64_e32 v[188:189], v[156:157]
	v_mov_b64_e32 v[186:187], v[154:155]
	v_mov_b64_e32 v[184:185], v[152:153]
	v_mov_b64_e32 v[182:183], v[150:151]
	v_mov_b64_e32 v[180:181], v[148:149]
	v_mov_b64_e32 v[170:171], v[138:139]
	v_mov_b64_e32 v[168:169], v[136:137]
	v_mov_b64_e32 v[166:167], v[134:135]
	v_mov_b64_e32 v[164:165], v[132:133]
	v_mov_b64_e32 v[162:163], v[130:131]
	v_mov_b64_e32 v[160:161], v[128:129]
	v_mov_b64_e32 v[178:179], v[146:147]
	v_mov_b64_e32 v[176:177], v[144:145]
	v_mov_b64_e32 v[76:77], v[140:141]
	v_mov_b64_e32 v[78:79], v[142:143]
	v_mov_b64_e32 v[32:33], v[64:65]
	v_mov_b64_e32 v[52:53], v[84:85]
	v_mov_b64_e32 v[54:55], v[86:87]
	v_mov_b64_e32 v[62:63], v[94:95]
	v_mov_b64_e32 v[34:35], v[66:67]
	v_mov_b64_e32 v[36:37], v[68:69]
	v_mov_b64_e32 v[38:39], v[70:71]
	v_mov_b64_e32 v[40:41], v[72:73]
	v_mov_b64_e32 v[42:43], v[74:75]
	v_mov_b64_e32 v[44:45], v[76:77]
	v_mov_b64_e32 v[46:47], v[78:79]
	v_mov_b64_e32 v[48:49], v[80:81]
	v_mov_b64_e32 v[50:51], v[82:83]
	v_mov_b64_e32 v[56:57], v[88:89]
	v_mov_b64_e32 v[58:59], v[90:91]
	v_mov_b64_e32 v[60:61], v[92:93]
	v_mov_b32_e32 v52, s7
	v_mov_b32_e32 v53, s7
	v_mov_b32_e32 v54, s7
	v_mov_b32_e32 v55, s7
	v_mov_b64_e32 v[126:127], v[62:63]
	v_mov_b64_e32 v[122:123], v[58:59]
	v_mov_b64_e32 v[120:121], v[56:57]
	v_mov_b64_e32 v[96:97], v[32:33]
	v_mov_b64_e32 v[124:125], v[60:61]
	v_mov_b64_e32 v[118:119], v[54:55]
	v_mov_b64_e32 v[116:117], v[52:53]
	v_mov_b64_e32 v[114:115], v[50:51]
	v_mov_b64_e32 v[112:113], v[48:49]
	v_mov_b64_e32 v[110:111], v[46:47]
	v_mov_b64_e32 v[108:109], v[44:45]
	v_mov_b64_e32 v[106:107], v[42:43]
	v_mov_b64_e32 v[104:105], v[40:41]
	v_mov_b64_e32 v[102:103], v[38:39]
	v_mov_b64_e32 v[100:101], v[36:37]
	v_mov_b64_e32 v[98:99], v[34:35]
	v_mov_b32_e32 v120, s7
	v_mov_b32_e32 v121, s7
	v_mov_b32_e32 v122, s7
	v_mov_b32_e32 v123, s7
	v_mov_b64_e32 v[0:1], v[96:97]
	v_mov_b64_e32 v[28:29], v[124:125]
	v_mov_b64_e32 v[30:31], v[126:127]
	v_mov_b64_e32 v[2:3], v[98:99]
	v_mov_b64_e32 v[4:5], v[100:101]
	v_mov_b64_e32 v[6:7], v[102:103]
	v_mov_b64_e32 v[8:9], v[104:105]
	v_mov_b64_e32 v[10:11], v[106:107]
	v_mov_b64_e32 v[12:13], v[108:109]
	v_mov_b64_e32 v[14:15], v[110:111]
	v_mov_b64_e32 v[16:17], v[112:113]
	v_mov_b64_e32 v[18:19], v[114:115]
	v_mov_b64_e32 v[20:21], v[116:117]
	v_mov_b64_e32 v[22:23], v[118:119]
	v_mov_b64_e32 v[24:25], v[120:121]
	v_mov_b64_e32 v[26:27], v[122:123]
	v_mov_b32_e32 v28, s7
	v_mov_b32_e32 v29, s7
	v_mov_b32_e32 v30, s7
	v_mov_b32_e32 v31, s7
	v_mov_b64_e32 v[174:175], v[142:143]
	v_mov_b64_e32 v[172:173], v[140:141]
	s_or_b64 exec, exec, s[0:1]
	v_cmp_gt_i32_e32 vcc, s18, v206
	s_and_saveexec_b64 s[0:1], vcc
	s_cbranch_execz .LBB0_470
.LBB0_546:
	v_add_u32_e32 v0, 32, v206
	v_mad_i64_i32 v[0:1], s[4:5], v0, s21, v[204:205]
	global_load_dwordx4 v[176:179], v[0:1], off nt
	s_waitcnt vmcnt(0)
	v_mov_b64_e32 v[32:33], v[160:161]
	v_mov_b64_e32 v[52:53], v[180:181]
	v_mov_b64_e32 v[54:55], v[182:183]
	v_mov_b64_e32 v[62:63], v[190:191]
	v_mov_b64_e32 v[34:35], v[162:163]
	v_mov_b64_e32 v[36:37], v[164:165]
	v_mov_b64_e32 v[38:39], v[166:167]
	v_mov_b64_e32 v[40:41], v[168:169]
	v_mov_b64_e32 v[42:43], v[170:171]
	v_mov_b64_e32 v[44:45], v[172:173]
	v_mov_b64_e32 v[46:47], v[174:175]
	v_mov_b64_e32 v[56:57], v[184:185]
	v_mov_b64_e32 v[58:59], v[186:187]
	v_mov_b64_e32 v[60:61], v[188:189]
	v_mov_b32_e32 v52, s7
	v_mov_b32_e32 v53, s7
	v_mov_b32_e32 v54, s7
	v_mov_b32_e32 v55, s7
	v_mov_b64_e32 v[64:65], v[160:161]
	v_mov_b64_e32 v[66:67], v[162:163]
	v_mov_b64_e32 v[68:69], v[164:165]
	v_mov_b64_e32 v[70:71], v[166:167]
	v_mov_b64_e32 v[72:73], v[168:169]
	v_mov_b64_e32 v[74:75], v[170:171]
	v_mov_b64_e32 v[76:77], v[172:173]
	v_mov_b64_e32 v[78:79], v[174:175]
	v_mov_b64_e32 v[88:89], v[184:185]
	v_mov_b64_e32 v[90:91], v[186:187]
	v_mov_b64_e32 v[92:93], v[188:189]
	v_mov_b64_e32 v[94:95], v[190:191]
	v_mov_b64_e32 v[84:85], v[180:181]
	v_mov_b64_e32 v[86:87], v[182:183]
	v_mov_b64_e32 v[48:49], v[176:177]
	v_mov_b64_e32 v[50:51], v[178:179]
	v_mov_b64_e32 v[126:127], v[62:63]
	v_mov_b64_e32 v[122:123], v[58:59]
	v_mov_b64_e32 v[120:121], v[56:57]
	v_mov_b64_e32 v[96:97], v[32:33]
	v_mov_b64_e32 v[124:125], v[60:61]
	v_mov_b64_e32 v[118:119], v[54:55]
	v_mov_b64_e32 v[116:117], v[52:53]
	v_mov_b64_e32 v[114:115], v[50:51]
	v_mov_b64_e32 v[112:113], v[48:49]
	v_mov_b64_e32 v[110:111], v[46:47]
	v_mov_b64_e32 v[108:109], v[44:45]
	v_mov_b64_e32 v[106:107], v[42:43]
	v_mov_b64_e32 v[104:105], v[40:41]
	v_mov_b64_e32 v[102:103], v[38:39]
	v_mov_b64_e32 v[100:101], v[36:37]
	v_mov_b64_e32 v[98:99], v[34:35]
	v_mov_b32_e32 v120, s7
	v_mov_b32_e32 v121, s7
	v_mov_b32_e32 v122, s7
	v_mov_b32_e32 v123, s7
	v_mov_b64_e32 v[0:1], v[96:97]
	v_mov_b64_e32 v[28:29], v[124:125]
	v_mov_b64_e32 v[30:31], v[126:127]
	v_mov_b64_e32 v[2:3], v[98:99]
	v_mov_b64_e32 v[4:5], v[100:101]
	v_mov_b64_e32 v[6:7], v[102:103]
	v_mov_b64_e32 v[8:9], v[104:105]
	v_mov_b64_e32 v[10:11], v[106:107]
	v_mov_b64_e32 v[12:13], v[108:109]
	v_mov_b64_e32 v[14:15], v[110:111]
	v_mov_b64_e32 v[16:17], v[112:113]
	v_mov_b64_e32 v[18:19], v[114:115]
	v_mov_b64_e32 v[20:21], v[116:117]
	v_mov_b64_e32 v[22:23], v[118:119]
	v_mov_b64_e32 v[24:25], v[120:121]
	v_mov_b64_e32 v[26:27], v[122:123]
	v_mov_b32_e32 v28, s7
	v_mov_b32_e32 v29, s7
	v_mov_b32_e32 v30, s7
	v_mov_b32_e32 v31, s7
	v_mov_b64_e32 v[80:81], v[176:177]
	v_mov_b64_e32 v[82:83], v[178:179]
	s_or_b64 exec, exec, s[0:1]
	v_cmp_gt_i32_e32 vcc, s25, v206
	s_and_saveexec_b64 s[0:1], vcc
	s_cbranch_execz .LBB0_471
.LBB0_547:
	v_add_u32_e32 v0, 40, v206
	v_mad_i64_i32 v[0:1], s[4:5], v0, s21, v[204:205]
	global_load_dwordx4 v[84:87], v[0:1], off nt
	s_waitcnt vmcnt(0)
	v_mov_b64_e32 v[126:127], v[94:95]
	v_mov_b64_e32 v[122:123], v[90:91]
	v_mov_b64_e32 v[120:121], v[88:89]
	v_mov_b64_e32 v[96:97], v[64:65]
	v_mov_b64_e32 v[124:125], v[92:93]
	v_mov_b64_e32 v[114:115], v[82:83]
	v_mov_b64_e32 v[112:113], v[80:81]
	v_mov_b64_e32 v[110:111], v[78:79]
	v_mov_b64_e32 v[108:109], v[76:77]
	v_mov_b64_e32 v[106:107], v[74:75]
	v_mov_b64_e32 v[104:105], v[72:73]
	v_mov_b64_e32 v[102:103], v[70:71]
	v_mov_b64_e32 v[100:101], v[68:69]
	v_mov_b64_e32 v[98:99], v[66:67]
	v_mov_b32_e32 v120, s7
	v_mov_b32_e32 v121, s7
	v_mov_b32_e32 v122, s7
	v_mov_b32_e32 v123, s7
	v_mov_b64_e32 v[32:33], v[64:65]
	v_mov_b64_e32 v[34:35], v[66:67]
	v_mov_b64_e32 v[36:37], v[68:69]
	v_mov_b64_e32 v[38:39], v[70:71]
	v_mov_b64_e32 v[40:41], v[72:73]
	v_mov_b64_e32 v[42:43], v[74:75]
	v_mov_b64_e32 v[44:45], v[76:77]
	v_mov_b64_e32 v[46:47], v[78:79]
	v_mov_b64_e32 v[48:49], v[80:81]
	v_mov_b64_e32 v[50:51], v[82:83]
	v_mov_b64_e32 v[60:61], v[92:93]
	v_mov_b64_e32 v[62:63], v[94:95]
	v_mov_b64_e32 v[56:57], v[88:89]
	v_mov_b64_e32 v[58:59], v[90:91]
	v_mov_b64_e32 v[118:119], v[86:87]
	v_mov_b64_e32 v[116:117], v[84:85]
	v_mov_b64_e32 v[0:1], v[96:97]
	v_mov_b64_e32 v[28:29], v[124:125]
	v_mov_b64_e32 v[30:31], v[126:127]
	v_mov_b64_e32 v[2:3], v[98:99]
	v_mov_b64_e32 v[4:5], v[100:101]
	v_mov_b64_e32 v[6:7], v[102:103]
	v_mov_b64_e32 v[8:9], v[104:105]
	v_mov_b64_e32 v[10:11], v[106:107]
	v_mov_b64_e32 v[12:13], v[108:109]
	v_mov_b64_e32 v[14:15], v[110:111]
	v_mov_b64_e32 v[16:17], v[112:113]
	v_mov_b64_e32 v[18:19], v[114:115]
	v_mov_b64_e32 v[20:21], v[116:117]
	v_mov_b64_e32 v[22:23], v[118:119]
	v_mov_b64_e32 v[24:25], v[120:121]
	v_mov_b64_e32 v[26:27], v[122:123]
	v_mov_b32_e32 v28, s7
	v_mov_b32_e32 v29, s7
	v_mov_b32_e32 v30, s7
	v_mov_b32_e32 v31, s7
	v_mov_b64_e32 v[52:53], v[84:85]
	v_mov_b64_e32 v[54:55], v[86:87]
	s_or_b64 exec, exec, s[0:1]
	v_cmp_gt_i32_e32 vcc, s26, v206
	s_and_saveexec_b64 s[0:1], vcc
	s_cbranch_execz .LBB0_472
.LBB0_548:
	v_add_u32_e32 v0, 48, v206
	v_mad_i64_i32 v[0:1], s[4:5], v0, s21, v[204:205]
	global_load_dwordx4 v[56:59], v[0:1], off nt
	s_waitcnt vmcnt(0)
	v_mov_b64_e32 v[0:1], v[32:33]
	v_mov_b64_e32 v[28:29], v[60:61]
	v_mov_b64_e32 v[30:31], v[62:63]
	v_mov_b64_e32 v[126:127], v[62:63]
	v_mov_b64_e32 v[2:3], v[34:35]
	v_mov_b64_e32 v[4:5], v[36:37]
	v_mov_b64_e32 v[6:7], v[38:39]
	v_mov_b64_e32 v[8:9], v[40:41]
	v_mov_b64_e32 v[10:11], v[42:43]
	v_mov_b64_e32 v[12:13], v[44:45]
	v_mov_b64_e32 v[14:15], v[46:47]
	v_mov_b64_e32 v[16:17], v[48:49]
	v_mov_b64_e32 v[18:19], v[50:51]
	v_mov_b64_e32 v[20:21], v[52:53]
	v_mov_b64_e32 v[22:23], v[54:55]
	v_mov_b32_e32 v28, s7
	v_mov_b32_e32 v29, s7
	v_mov_b32_e32 v30, s7
	v_mov_b32_e32 v31, s7
	v_mov_b64_e32 v[118:119], v[54:55]
	v_mov_b64_e32 v[116:117], v[52:53]
	v_mov_b64_e32 v[114:115], v[50:51]
	v_mov_b64_e32 v[112:113], v[48:49]
	v_mov_b64_e32 v[110:111], v[46:47]
	v_mov_b64_e32 v[108:109], v[44:45]
	v_mov_b64_e32 v[106:107], v[42:43]
	v_mov_b64_e32 v[104:105], v[40:41]
	v_mov_b64_e32 v[102:103], v[38:39]
	v_mov_b64_e32 v[100:101], v[36:37]
	v_mov_b64_e32 v[98:99], v[34:35]
	v_mov_b64_e32 v[96:97], v[32:33]
	v_mov_b64_e32 v[124:125], v[60:61]
	v_mov_b64_e32 v[24:25], v[56:57]
	v_mov_b64_e32 v[26:27], v[58:59]
	v_mov_b64_e32 v[122:123], v[58:59]
	v_mov_b64_e32 v[120:121], v[56:57]
	s_or_b64 exec, exec, s[0:1]
	v_cmp_gt_i32_e32 vcc, s27, v206
	s_and_saveexec_b64 s[0:1], vcc
	s_cbranch_execnz .LBB0_473
	s_branch .LBB0_474
